# m3pf: M3 S/num MFMA sections prefetch their LDS operands into fresh registers with counted lgkmcnt (was one LDS latency per MFMA)
# baseline (speedup 1.0000x reference)
;   __host__ __device__ __forceinline__ bf16_t* ACT() const { return (bf16_t*)(wsl() + OFF_ACT); }
; __device__ __forceinline__ float bf2f(bf16_t h) { return __uint_as_float(((uint32_t)h) << 16); }
; #define MFMA16(a, b, c) __builtin_amdgcn_mfma_f32_16x16x32_bf16(a, b, c, 0, 0, 0)
; __device__ __forceinline__ void m3_phase(const Params& p, char* smem) {
;     ...
;       {
;         const int mi = w & 3, nh = w >> 2;
;         f32x4 a1[4], a2[4];
; #pragma unroll
;         for (int q = 0; q < 4; ++q) { a1[q] = (f32x4){0.f, 0.f, 0.f, 0.f}; a2[q] = (f32x4){0.f, 0.f, 0.f, 0.f}; }
; #pragma unroll
;         for (int ks = 0; ks < 2; ++ks) {
;           bf16x8 a = *(const bf16x8*)(Sw + (mi * 16 + fr) * 72 + ks * 32 + fq * 8);
; #pragma unroll
;           for (int q = 0; q < 4; ++q) {
;             bf16x8 bb = *(const bf16x8*)(Vt + ((nh * 4 + q) * 16 + fr) * 72 + ks * 32 + fq * 8);
;             a1[q] = MFMA16(a, bb, a1[q]);
;           }
;         }
; #pragma unroll
;         for (int ks = 0; ks < 4; ++ks) {
;           bf16x8 a = *(const bf16x8*)(Qs + (mi * 16 + fr) * 136 + ks * 32 + fq * 8);
; #pragma unroll
;           for (int q = 0; q < 4; ++q) {
;             bf16x8 bb = *(const bf16x8*)(Cs + ((nh * 4 + q) * 16 + fr) * 136 + ks * 32 + fq * 8);
;             a2[q] = MFMA16(a, bb, a2[q]);
;           }
;         }
; #pragma unroll
;         for (int jj = 0; jj < 4; ++jj) {
;           int t = mi * 16 + fq * 4 + jj;
;           float wi = wint[t];
;           float den = denp[t] + denp[64 + t] + wi * qn[t];
;           float inv = 1.0f / fmaxf(fabsf(den), emt[t]);
;           int tl = (dir == 0) ? t : (63 - t);
; #pragma unroll
;           for (int q = 0; q < 4; ++q) {
;             int v = (nh * 4 + q) * 16 + fr;
;             float hv = (a1[q][jj] + wi * a2[q][jj]) * inv;
;             if (dir == 0) hs[tl * 132 + v] = hv; else hs[tl * 132 + v] += hv;
;           }
;         }
;     ...
;     for (int q = 0; q < 8; ++q) {
;       int tl = w * 8 + q;
;       float v0 = hs[tl * 132 + lane], v1 = hs[tl * 132 + 64 + lane];
;       float ss = wave_sum(v0 * v0 + v1 * v1);
;       float rstd = rsqrtf(ss * (1.0f / 128.0f) + 1e-6f);
;       int row = rowbase + c * 64 + tl;
;       const bf16_t* po = p.ACT() + (size_t)row * PW + 2208 + h * 128;
;       float o0 = bf2f(po[lane]), o1 = bf2f(po[64 + lane]);
;       float y0 = v0 * rstd * p.mlstm_out_g[h * 128 + lane] * sigmoidf_(o0);
.LBB0_484:
	s_or_b64 exec, exec, s[2:3]
	s_waitcnt lgkmcnt(0)
	s_barrier
	s_mov_b64 s[14:15], 0x7291140
	s_add_u32 s94, s5, s30
	s_addc_u32 s95, s6, 0
	s_brev_b32 s16, 60
	s_mov_b32 s12, 0x800000
	s_add_i32 s4, s4, s80
	s_sub_i32 s10, s10, s80
	s_movk_i32 s84, 0x1600
	s_cmpk_gt_i32 s4, 0x41f
	ds_read_b128 v[160:163], v59
	ds_read_b128 v[172:175], v142 offset:34816
	ds_read_b128 v[196:199], v142 offset:37120
	ds_read_b128 v[200:203], v142 offset:39424
	ds_read_b128 v[204:207], v142 offset:41728
	ds_read_b128 v[208:211], v59 offset:64
	ds_read_b128 v[212:215], v142 offset:34880
	ds_read_b128 v[236:239], v142 offset:37184
	ds_read_b128 v[240:243], v142 offset:39488
	ds_read_b128 v[244:247], v142 offset:41792
	s_waitcnt lgkmcnt(6)
	v_mfma_f32_16x16x32_bf16 v[20:23], v[160:163], v[200:203], 0
	ds_read_b128 v[248:251], v52
	v_mfma_f32_16x16x32_bf16 v[4:7], v[160:163], v[172:175], 0
	ds_read_b128 v[200:203], v150 offset:53248
	v_mfma_f32_16x16x32_bf16 v[8:11], v[160:163], v[196:199], 0
	ds_read_b128 v[172:175], v150 offset:57600
	s_waitcnt lgkmcnt(8)
	v_mfma_f32_16x16x32_bf16 v[0:3], v[160:163], v[204:207], 0
	ds_read_b128 v[196:199], v143 offset:61952
	ds_read_b128 v[160:163], v150 offset:61952
	s_waitcnt lgkmcnt(8)
	v_mfma_f32_16x16x32_bf16 v[12:15], v[208:211], v[212:215], v[4:7]
	ds_read_b128 v[204:207], v52 offset:64
	s_waitcnt lgkmcnt(8)
	v_mfma_f32_16x16x32_bf16 v[16:19], v[208:211], v[236:239], v[8:11]
	ds_read_b128 v[212:215], v150 offset:53312
	s_waitcnt lgkmcnt(8)
	v_mfma_f32_16x16x32_bf16 v[4:7], v[208:211], v[240:243], v[20:23]
	ds_read_b128 v[236:239], v150 offset:57664
	s_waitcnt lgkmcnt(8)
	v_mfma_f32_16x16x32_bf16 v[0:3], v[208:211], v[244:247], v[0:3]
	ds_read_b128 v[240:243], v150 offset:62016
	ds_read_b128 v[208:211], v143 offset:62016
	s_waitcnt lgkmcnt(8)
	v_mfma_f32_16x16x32_bf16 v[20:23], v[248:251], v[200:203], 0
	ds_read_b128 v[244:247], v52 offset:128
	s_waitcnt lgkmcnt(8)
	v_mfma_f32_16x16x32_bf16 v[24:27], v[248:251], v[172:175], 0
	ds_read_b128 v[200:203], v150 offset:53376
	s_waitcnt lgkmcnt(7)
	v_mfma_f32_16x16x32_bf16 v[28:31], v[248:251], v[160:163], 0
	ds_read_b128 v[172:175], v150 offset:57728
	v_mfma_f32_16x16x32_bf16 v[8:11], v[248:251], v[196:199], 0
	ds_read_b128 v[160:163], v150 offset:62080
	ds_read_b128 v[248:251], v143 offset:62080
	s_waitcnt lgkmcnt(8)
	v_mfma_f32_16x16x32_bf16 v[20:23], v[204:207], v[212:215], v[20:23]
	ds_read_b128 v[196:199], v52 offset:192
	s_waitcnt lgkmcnt(8)
	v_mfma_f32_16x16x32_bf16 v[24:27], v[204:207], v[236:239], v[24:27]
	ds_read_b128 v[212:215], v150 offset:53440
	s_waitcnt lgkmcnt(8)
	v_mfma_f32_16x16x32_bf16 v[28:31], v[204:207], v[240:243], v[28:31]
	ds_read_b128 v[236:239], v150 offset:57792
	s_waitcnt lgkmcnt(8)
	v_mfma_f32_16x16x32_bf16 v[8:11], v[204:207], v[208:211], v[8:11]
	ds_read_b128 v[240:243], v150 offset:62144
	ds_read_b128 v[204:207], v143 offset:62144
	s_waitcnt lgkmcnt(8)
	v_mfma_f32_16x16x32_bf16 v[20:23], v[244:247], v[200:203], v[20:23]
	s_waitcnt lgkmcnt(7)
	v_mfma_f32_16x16x32_bf16 v[24:27], v[244:247], v[172:175], v[24:27]
	s_waitcnt lgkmcnt(6)
	v_mfma_f32_16x16x32_bf16 v[152:155], v[244:247], v[160:163], v[28:31]
	s_waitcnt lgkmcnt(5)
	v_mfma_f32_16x16x32_bf16 v[8:11], v[244:247], v[248:251], v[8:11]
	s_waitcnt lgkmcnt(3)
	v_mfma_f32_16x16x32_bf16 v[28:31], v[196:199], v[212:215], v[20:23]
	s_waitcnt lgkmcnt(2)
	v_mfma_f32_16x16x32_bf16 v[24:27], v[196:199], v[236:239], v[24:27]
	s_waitcnt lgkmcnt(1)
	v_mfma_f32_16x16x32_bf16 v[20:23], v[196:199], v[240:243], v[152:155]
	s_waitcnt lgkmcnt(0)
	v_mfma_f32_16x16x32_bf16 v[8:11], v[196:199], v[204:207], v[8:11]
	ds_read_b32 v148, v98
	ds_read2st64_b32 v[146:147], v99 offset1:1
	s_waitcnt lgkmcnt(1)
	v_fma_f32 v12, v28, v148, v12
	s_waitcnt lgkmcnt(0)
	v_add_f32_e32 v146, v146, v147
	ds_read_b32 v147, v100
	v_fma_f32 v16, v24, v148, v16
	v_fma_f32 v4, v20, v148, v4
	v_fma_f32 v0, v148, v8, v0
	s_waitcnt lgkmcnt(0)
	v_fmac_f32_e32 v146, v148, v147
	ds_read_b32 v147, v101
	s_waitcnt lgkmcnt(0)
	v_max_f32_e32 v147, v147, v147
	v_max_f32_e64 v146, |v146|, v147
	v_div_scale_f32 v147, s[2:3], v146, v146, 1.0
	v_rcp_f32_e32 v149, v147
	s_nop 0
	v_fma_f32 v150, -v147, v149, 1.0
	v_fmac_f32_e32 v149, v150, v149
	v_div_scale_f32 v150, vcc, 1.0, v146, 1.0
	v_mul_f32_e32 v151, v150, v149
	v_fma_f32 v152, -v147, v151, v150
	v_fmac_f32_e32 v151, v152, v149
	v_fma_f32 v147, -v147, v151, v150
	v_div_fmas_f32 v147, v147, v149, v151
	v_div_fixup_f32 v149, v147, v146, 1.0
	ds_read2_b32 v[146:147], v118 offset1:16
	s_waitcnt lgkmcnt(0)
	v_fma_f32 v12, v12, v149, v146
	v_fmac_f32_e32 v147, v16, v149
	ds_write2_b32 v118, v12, v147 offset1:16
	ds_read2_b32 v[146:147], v118 offset0:32 offset1:48
	s_waitcnt lgkmcnt(0)
	v_fma_f32 v4, v4, v149, v146
	v_fmac_f32_e32 v147, v0, v149
	ds_write2_b32 v118, v4, v147 offset0:32 offset1:48
	ds_read_b32 v0, v103
	ds_read_b32 v4, v104
	ds_read_b32 v8, v105
	ds_read2st64_b32 v[146:147], v106 offset1:1
	s_waitcnt lgkmcnt(2)
	v_max_f32_e32 v4, v4, v4
	s_waitcnt lgkmcnt(0)
	v_add_f32_e32 v12, v147, v146
	v_fmac_f32_e32 v12, v0, v8
	v_max_f32_e64 v4, |v12|, v4
	v_div_scale_f32 v8, s[2:3], v4, v4, 1.0
	v_rcp_f32_e32 v12, v8
	s_nop 0
	v_fma_f32 v16, -v8, v12, 1.0
	v_fmac_f32_e32 v12, v16, v12
	v_div_scale_f32 v16, vcc, 1.0, v4, 1.0
	v_mul_f32_e32 v20, v16, v12
	v_fma_f32 v24, -v8, v20, v16
	v_fmac_f32_e32 v20, v24, v12
	v_fma_f32 v8, -v8, v20, v16
	v_div_fmas_f32 v8, v8, v12, v20
	v_div_fixup_f32 v8, v8, v4, 1.0
	v_fma_f32 v4, v29, v0, v13
	ds_read2_b32 v[12:13], v119 offset1:16
	s_waitcnt lgkmcnt(0)
;   __host__ __device__ __forceinline__ bf16_t* ACT() const { return (bf16_t*)(wsl() + OFF_ACT); }
; __device__ __forceinline__ float bf2f(bf16_t h) { return __uint_as_float(((uint32_t)h) << 16); }
; __device__ __forceinline__ void m3_phase(const Params& p, char* smem) {
;     ...
;         for (int jj = 0; jj < 4; ++jj) {
;           int t = mi * 16 + fq * 4 + jj;
;           float wi = wint[t];
;           float den = denp[t] + denp[64 + t] + wi * qn[t];
;           float inv = 1.0f / fmaxf(fabsf(den), emt[t]);
;           int tl = (dir == 0) ? t : (63 - t);
; #pragma unroll
;           for (int q = 0; q < 4; ++q) {
;             int v = (nh * 4 + q) * 16 + fr;
;             float hv = (a1[q][jj] + wi * a2[q][jj]) * inv;
;             if (dir == 0) hs[tl * 132 + v] = hv; else hs[tl * 132 + v] += hv;
;           }
;         }
;     ...
;     for (int q = 0; q < 8; ++q) {
;       int tl = w * 8 + q;
;       float v0 = hs[tl * 132 + lane], v1 = hs[tl * 132 + 64 + lane];
;       float ss = wave_sum(v0 * v0 + v1 * v1);
;       float rstd = rsqrtf(ss * (1.0f / 128.0f) + 1e-6f);
;       int row = rowbase + c * 64 + tl;
;       const bf16_t* po = p.ACT() + (size_t)row * PW + 2208 + h * 128;
;       float o0 = bf2f(po[lane]), o1 = bf2f(po[64 + lane]);
	v_fma_f32 v4, v4, v8, v12
	v_fma_f32 v12, v25, v0, v17
	v_fmac_f32_e32 v13, v12, v8
	ds_write2_b32 v119, v4, v13 offset1:16
	v_fma_f32 v12, v21, v0, v5
	ds_read2_b32 v[4:5], v119 offset0:32 offset1:48
	v_fma_f32 v0, v9, v0, v1
	s_waitcnt lgkmcnt(0)
	v_fma_f32 v4, v12, v8, v4
	v_fmac_f32_e32 v5, v0, v8
	ds_write2_b32 v119, v4, v5 offset0:32 offset1:48
	ds_read_b32 v4, v108
	ds_read_b32 v5, v109
	ds_read_b32 v8, v110
	ds_read2st64_b32 v[0:1], v111 offset1:1
	s_waitcnt lgkmcnt(3)
	v_fma_f32 v6, v22, v4, v6
	v_fma_f32 v2, v10, v4, v2
	s_waitcnt lgkmcnt(0)
	v_add_f32_e32 v0, v1, v0
	v_fmac_f32_e32 v0, v4, v8
	v_max_f32_e32 v1, v5, v5
	v_max_f32_e64 v0, |v0|, v1
	v_div_scale_f32 v1, s[2:3], v0, v0, 1.0
	v_rcp_f32_e32 v5, v1
	s_nop 0
	v_fma_f32 v8, -v1, v5, 1.0
	v_fmac_f32_e32 v5, v8, v5
	v_div_scale_f32 v8, vcc, 1.0, v0, 1.0
	v_mul_f32_e32 v9, v8, v5
	v_fma_f32 v12, -v1, v9, v8
	v_fmac_f32_e32 v9, v12, v5
	v_fma_f32 v1, -v1, v9, v8
	v_div_fmas_f32 v1, v1, v5, v9
	v_div_fixup_f32 v5, v1, v0, 1.0
	ds_read2_b32 v[0:1], v120 offset1:16
	v_fma_f32 v8, v30, v4, v14
	s_waitcnt lgkmcnt(0)
	v_fma_f32 v0, v8, v5, v0
	v_fma_f32 v8, v26, v4, v18
	v_fmac_f32_e32 v1, v8, v5
	ds_write2_b32 v120, v0, v1 offset1:16
	ds_read2_b32 v[0:1], v120 offset0:32 offset1:48
	s_waitcnt lgkmcnt(0)
	v_fma_f32 v0, v6, v5, v0
	v_fmac_f32_e32 v1, v2, v5
	ds_write2_b32 v120, v0, v1 offset0:32 offset1:48
	ds_read_b32 v2, v113
	ds_read_b32 v4, v114
	ds_read_b32 v5, v115
	ds_read2st64_b32 v[0:1], v116 offset1:1
	s_waitcnt lgkmcnt(3)
	v_fmac_f32_e32 v15, v31, v2
	v_fmac_f32_e32 v19, v27, v2
	v_fmac_f32_e32 v7, v23, v2
	s_waitcnt lgkmcnt(0)
	v_add_f32_e32 v0, v1, v0
	v_fmac_f32_e32 v0, v2, v5
	v_max_f32_e32 v1, v4, v4
	v_max_f32_e64 v0, |v0|, v1
	v_div_scale_f32 v1, s[2:3], v0, v0, 1.0
	v_rcp_f32_e32 v4, v1
	v_fmac_f32_e32 v3, v11, v2
	v_add_u32_e32 v2, s11, v66
	s_mov_b32 s11, 0x7291000
	v_fma_f32 v5, -v1, v4, 1.0
	v_fmac_f32_e32 v4, v5, v4
	v_div_scale_f32 v5, vcc, 1.0, v0, 1.0
	v_mul_f32_e32 v6, v5, v4
	v_fma_f32 v8, -v1, v6, v5
	v_fmac_f32_e32 v6, v8, v4
	v_fma_f32 v1, -v1, v6, v5
	v_div_fmas_f32 v1, v1, v4, v6
	v_div_fixup_f32 v4, v1, v0, 1.0
	ds_read2_b32 v[0:1], v121 offset1:16
	s_waitcnt lgkmcnt(0)
	v_fma_f32 v0, v15, v4, v0
	v_fmac_f32_e32 v1, v19, v4
	ds_write2_b32 v121, v0, v1 offset1:16
	ds_read2_b32 v[0:1], v121 offset0:32 offset1:48
	s_waitcnt lgkmcnt(0)
	v_fma_f32 v0, v7, v4, v0
	v_fmac_f32_e32 v1, v3, v4
	ds_write2_b32 v121, v0, v1 offset0:32 offset1:48
	v_or_b32_e32 v0, s13, v34
	v_lshlrev_b32_e32 v0, 2, v0
	s_waitcnt lgkmcnt(0)
	s_barrier
	global_load_dword v13, v0, s[86:87]
	global_load_dword v12, v0, s[86:87] offset:256
	v_mov_b64_e32 v[0:1], s[88:89]
	s_movk_i32 s13, 0x1600
	v_mad_i64_i32 v[6:7], s[2:3], v2, s13, v[0:1]
	v_lshl_add_u64 v[6:7], v[6:7], 0, s[30:31]
	v_lshl_add_u64 v[6:7], v[6:7], 0, v[166:167]
	v_lshl_add_u64 v[10:11], v[6:7], 0, s[14:15]
	v_add_co_u32_e32 v6, vcc, s11, v6
	ds_read_b32 v8, v69
	ds_read_b32 v9, v122 offset:256
	v_addc_co_u32_e32 v7, vcc, 0, v7, vcc
	v_add_co_u32_e32 v180, vcc, 0x1600, v6
	s_nop 1
	v_addc_co_u32_e32 v181, vcc, 0, v7, vcc
	global_load_ushort v182, v[180:181], off offset:320
	v_add_co_u32_e32 v180, vcc, 0x1600, v10
	s_nop 1
	v_addc_co_u32_e32 v181, vcc, 0, v11, vcc
	global_load_ushort v183, v[180:181], off offset:128
	v_add_co_u32_e32 v180, vcc, 0x2c00, v6
	s_nop 1
	v_addc_co_u32_e32 v181, vcc, 0, v7, vcc
	global_load_ushort v184, v[180:181], off offset:320
	v_add_co_u32_e32 v180, vcc, 0x2c00, v10
	s_nop 1
	v_addc_co_u32_e32 v181, vcc, 0, v11, vcc
	global_load_ushort v185, v[180:181], off offset:128
	v_add_co_u32_e32 v180, vcc, 0x4200, v6
	s_nop 1
	v_addc_co_u32_e32 v181, vcc, 0, v7, vcc
	global_load_ushort v186, v[180:181], off offset:320
	v_add_co_u32_e32 v180, vcc, 0x4200, v10
	s_nop 1
	v_addc_co_u32_e32 v181, vcc, 0, v11, vcc
	global_load_ushort v187, v[180:181], off offset:128
	v_add_co_u32_e32 v180, vcc, 0x5800, v6
	s_nop 1
	v_addc_co_u32_e32 v181, vcc, 0, v7, vcc
	global_load_ushort v188, v[180:181], off offset:320
	v_add_co_u32_e32 v180, vcc, 0x5800, v10
	s_nop 1
	v_addc_co_u32_e32 v181, vcc, 0, v11, vcc
	global_load_ushort v189, v[180:181], off offset:128
	v_add_co_u32_e32 v180, vcc, 0x6e00, v6
	s_nop 1
	v_addc_co_u32_e32 v181, vcc, 0, v7, vcc
	global_load_ushort v190, v[180:181], off offset:320
	v_add_co_u32_e32 v180, vcc, 0x6e00, v10
	s_nop 1
	v_addc_co_u32_e32 v181, vcc, 0, v11, vcc
	global_load_ushort v191, v[180:181], off offset:128
	v_add_co_u32_e32 v180, vcc, 0x8400, v6
	s_nop 1
	v_addc_co_u32_e32 v181, vcc, 0, v7, vcc
	global_load_ushort v192, v[180:181], off offset:320
	v_add_co_u32_e32 v180, vcc, 0x8400, v10
	s_nop 1
	v_addc_co_u32_e32 v181, vcc, 0, v11, vcc
	global_load_ushort v193, v[180:181], off offset:128
	v_add_co_u32_e32 v180, vcc, 0x9a00, v6
	s_nop 1
	v_addc_co_u32_e32 v181, vcc, 0, v7, vcc
	global_load_ushort v194, v[180:181], off offset:320
	v_add_co_u32_e32 v180, vcc, 0x9a00, v10
	s_nop 1
	v_addc_co_u32_e32 v181, vcc, 0, v11, vcc
	global_load_ushort v195, v[180:181], off offset:128
	global_load_ushort v6, v[6:7], off offset:320
	v_ashrrev_i32_e32 v3, 31, v2
	global_load_ushort v7, v[10:11], off offset:128
	s_waitcnt lgkmcnt(0)
	v_pk_mul_f32 v[4:5], v[8:9], v[8:9]
	s_mov_b32 s2, 0x358637bd
	v_mov_b32_e32 v17, v4
	s_waitcnt vmcnt(1)
	v_lshlrev_b32_e32 v6, 16, v6
	v_mul_f32_e32 v6, 0xbfb8aa3b, v6
	v_exp_f32_e32 v6, v6
	s_waitcnt vmcnt(0)
	v_lshlrev_b32_e32 v7, 16, v7
	v_add_f32_e32 v6, 1.0, v6
	v_rcp_f32_e32 v18, v6
	v_mul_f32_e32 v6, 0xbfb8aa3b, v7
	v_exp_f32_e32 v6, v6
	s_nop 0
	v_add_f32_e32 v6, 1.0, v6
	v_rcp_f32_e32 v19, v6
	v_lshlrev_b64 v[6:7], 11, v[2:3]
	v_lshl_add_u64 v[6:7], s[94:95], 0, v[6:7]
	v_lshl_add_u64 v[10:11], v[6:7], 0, v[166:167]
	ds_read_b32 v6, v123
	ds_read_b32 v7, v124 offset:256
	s_waitcnt lgkmcnt(0)
;   __host__ __device__ __forceinline__ bf16_t* ACT() const { return (bf16_t*)(wsl() + OFF_ACT); }
; __device__ __forceinline__ float bf2f(bf16_t h) { return __uint_as_float(((uint32_t)h) << 16); }
; __device__ __forceinline__ float sigmoidf_(float x) { return __builtin_amdgcn_rcpf(1.0f + __expf(-x)); }
; __device__ __forceinline__ void m3_phase(const Params& p, char* smem) {
;     ...
;     for (int q = 0; q < 8; ++q) {
;       int tl = w * 8 + q;
;       float v0 = hs[tl * 132 + lane], v1 = hs[tl * 132 + 64 + lane];
;       float ss = wave_sum(v0 * v0 + v1 * v1);
;       float rstd = rsqrtf(ss * (1.0f / 128.0f) + 1e-6f);
;       int row = rowbase + c * 64 + tl;
;       const bf16_t* po = p.ACT() + (size_t)row * PW + 2208 + h * 128;
;       float o0 = bf2f(po[lane]), o1 = bf2f(po[64 + lane]);
;       float y0 = v0 * rstd * p.mlstm_out_g[h * 128 + lane] * sigmoidf_(o0);
;       float y1 = v1 * rstd * p.mlstm_out_g[h * 128 + 64 + lane] * sigmoidf_(o1);
;       MIX[(size_t)row * D + 512 + h * 128 + lane] = f2bf(y0);
;       MIX[(size_t)row * D + 512 + h * 128 + 64 + lane] = f2bf(y1);
	v_pk_mul_f32 v[14:15], v[6:7], v[6:7]
	s_nop 0
	v_mov_b32_e32 v16, v14
	v_mov_b32_e32 v4, v15
	v_pk_add_f32 v[4:5], v[16:17], v[4:5]
	ds_bpermute_b32 v15, v67, v5
	ds_bpermute_b32 v14, v67, v4
	s_waitcnt lgkmcnt(0)
	v_pk_add_f32 v[4:5], v[4:5], v[14:15]
	ds_bpermute_b32 v15, v68, v5
	ds_bpermute_b32 v14, v68, v4
	s_waitcnt lgkmcnt(0)
	v_pk_add_f32 v[4:5], v[4:5], v[14:15]
	ds_bpermute_b32 v15, v56, v5
	ds_bpermute_b32 v14, v56, v4
	s_waitcnt lgkmcnt(0)
	v_pk_add_f32 v[4:5], v[4:5], v[14:15]
	ds_bpermute_b32 v15, v55, v5
	ds_bpermute_b32 v14, v55, v4
	s_waitcnt lgkmcnt(0)
	v_pk_add_f32 v[4:5], v[4:5], v[14:15]
	ds_bpermute_b32 v15, v54, v5
	ds_bpermute_b32 v14, v54, v4
	s_waitcnt lgkmcnt(0)
	v_pk_add_f32 v[4:5], v[4:5], v[14:15]
	ds_bpermute_b32 v15, v53, v5
	ds_bpermute_b32 v14, v53, v4
	s_waitcnt lgkmcnt(0)
	v_pk_add_f32 v[14:15], v[4:5], v[14:15]
	v_mov_b64_e32 v[4:5], s[2:3]
	v_pk_fma_f32 v[14:15], v[14:15], s[16:17], v[4:5] op_sel_hi:[1,0,0]
	s_nop 0
	v_mul_f32_e32 v3, 0x4b800000, v15
	v_cmp_gt_f32_e64 s[78:79], s12, v15
	v_cmp_gt_f32_e32 vcc, s12, v14
	s_nop 0
	v_cndmask_b32_e64 v3, v15, v3, s[78:79]
	v_rsq_f32_e32 v3, v3
	s_nop 0
	v_mul_f32_e32 v15, 0x45800000, v3
	v_cndmask_b32_e64 v3, v3, v15, s[78:79]
	v_mul_f32_e32 v8, v8, v3
	v_mul_f32_e32 v8, v13, v8
	v_mul_f32_e32 v8, v18, v8
	v_mul_f32_e32 v3, v9, v3
	v_mul_f32_e32 v3, v12, v3
	v_bfe_u32 v9, v8, 16, 1
	v_mul_f32_e32 v3, v19, v3
	v_add3_u32 v8, v8, v9, s28
	global_store_short_d16_hi v[10:11], v8, off offset:1024
	v_bfe_u32 v8, v3, 16, 1
	v_add3_u32 v3, v3, v8, s28
	global_store_short_d16_hi v[10:11], v3, off offset:1152
	v_mul_f32_e32 v3, 0x4b800000, v14
	v_cndmask_b32_e32 v3, v14, v3, vcc
	v_rsq_f32_e32 v3, v3
	s_nop 0
	v_mul_f32_e32 v8, 0x45800000, v3
	v_cndmask_b32_e32 v3, v3, v8, vcc
	v_add_u32_e32 v8, 1, v2
	v_mad_i64_i32 v[10:11], s[2:3], v8, s13, v[0:1]
	v_lshl_add_u64 v[10:11], v[10:11], 0, s[30:31]
	v_lshl_add_u64 v[10:11], v[10:11], 0, v[166:167]
	v_lshl_add_u64 v[14:15], v[10:11], 0, s[14:15]
	v_add_co_u32_e32 v10, vcc, s11, v10
	v_mul_f32_e32 v6, v6, v3
	s_nop 0
	v_addc_co_u32_e32 v11, vcc, 0, v11, vcc
	v_mov_b32_e32 v10, v182
	v_mul_f32_e32 v3, v7, v3
	v_mov_b32_e32 v11, v183
	v_mul_f32_e32 v6, v13, v6
	v_mul_f32_e32 v3, v12, v3
	v_ashrrev_i32_e32 v9, 31, v8
	v_lshlrev_b32_e32 v10, 16, v10
	v_mul_f32_e32 v10, 0xbfb8aa3b, v10
	v_lshlrev_b32_e32 v11, 16, v11
	v_exp_f32_e32 v10, v10
	v_mul_f32_e32 v7, 0xbfb8aa3b, v11
	v_exp_f32_e32 v7, v7
	v_add_f32_e32 v10, 1.0, v10
	v_rcp_f32_e32 v10, v10
	v_add_f32_e32 v7, 1.0, v7
	v_rcp_f32_e32 v7, v7
	v_mul_f32_e32 v6, v10, v6
	v_mul_f32_e32 v3, v7, v3
	v_bfe_u32 v7, v6, 16, 1
	v_add3_u32 v10, v6, v7, s28
	v_lshlrev_b64 v[6:7], 11, v[8:9]
	v_lshl_add_u64 v[6:7], s[94:95], 0, v[6:7]
	v_bfe_u32 v8, v3, 16, 1
	v_lshl_add_u64 v[6:7], v[6:7], 0, v[166:167]
	v_add3_u32 v3, v3, v8, s28
	global_store_short_d16_hi v[6:7], v10, off offset:1024
	global_store_short_d16_hi v[6:7], v3, off offset:1152
	v_add_u32_e32 v6, 2, v2
	v_mad_i64_i32 v[14:15], s[2:3], v6, s13, v[0:1]
	v_lshl_add_u64 v[14:15], v[14:15], 0, s[30:31]
	v_lshl_add_u64 v[14:15], v[14:15], 0, v[166:167]
	v_lshl_add_u64 v[16:17], v[14:15], 0, s[14:15]
	v_add_co_u32_e32 v14, vcc, s11, v14
	ds_read_b32 v8, v125
	ds_read_b32 v9, v126 offset:256
	v_addc_co_u32_e32 v15, vcc, 0, v15, vcc
	v_mov_b32_e32 v3, v184
	v_ashrrev_i32_e32 v7, 31, v6
	v_mov_b32_e32 v14, v185
	v_lshlrev_b64 v[6:7], 11, v[6:7]
	v_lshl_add_u64 v[6:7], s[94:95], 0, v[6:7]
	s_waitcnt lgkmcnt(0)
	v_pk_mul_f32 v[10:11], v[8:9], v[8:9]
	v_lshlrev_b32_e32 v3, 16, v3
	v_mov_b32_e32 v19, v10
	v_lshlrev_b32_e32 v14, 16, v14
	v_mul_f32_e32 v14, 0xbfb8aa3b, v14
	v_exp_f32_e32 v14, v14
	v_mul_f32_e32 v3, 0xbfb8aa3b, v3
	v_exp_f32_e32 v3, v3
	v_add_f32_e32 v14, 1.0, v14
	v_rcp_f32_e32 v20, v14
	v_lshl_add_u64 v[14:15], v[6:7], 0, v[166:167]
	ds_read_b32 v6, v127
	ds_read_b32 v7, v128 offset:256
	v_add_f32_e32 v3, 1.0, v3
	v_rcp_f32_e32 v3, v3
	s_waitcnt lgkmcnt(0)
	v_pk_mul_f32 v[16:17], v[6:7], v[6:7]
	s_nop 0
	v_mov_b32_e32 v18, v16
	v_mov_b32_e32 v10, v17
	v_pk_add_f32 v[10:11], v[18:19], v[10:11]
	ds_bpermute_b32 v17, v67, v11
	ds_bpermute_b32 v16, v67, v10
	s_waitcnt lgkmcnt(0)
	v_pk_add_f32 v[10:11], v[10:11], v[16:17]
	ds_bpermute_b32 v17, v68, v11
	ds_bpermute_b32 v16, v68, v10
	s_waitcnt lgkmcnt(0)
	v_pk_add_f32 v[10:11], v[10:11], v[16:17]
	ds_bpermute_b32 v17, v56, v11
	ds_bpermute_b32 v16, v56, v10
	s_waitcnt lgkmcnt(0)
	v_pk_add_f32 v[10:11], v[10:11], v[16:17]
	ds_bpermute_b32 v17, v55, v11
	ds_bpermute_b32 v16, v55, v10
	s_waitcnt lgkmcnt(0)
	v_pk_add_f32 v[10:11], v[10:11], v[16:17]
	ds_bpermute_b32 v17, v54, v11
	ds_bpermute_b32 v16, v54, v10
	s_waitcnt lgkmcnt(0)
	v_pk_add_f32 v[10:11], v[10:11], v[16:17]
	ds_bpermute_b32 v17, v53, v11
	ds_bpermute_b32 v16, v53, v10
	s_waitcnt lgkmcnt(0)
;   __host__ __device__ __forceinline__ bf16_t* ACT() const { return (bf16_t*)(wsl() + OFF_ACT); }
; __device__ __forceinline__ float bf2f(bf16_t h) { return __uint_as_float(((uint32_t)h) << 16); }
; __device__ __forceinline__ float sigmoidf_(float x) { return __builtin_amdgcn_rcpf(1.0f + __expf(-x)); }
; __device__ __forceinline__ void m3_phase(const Params& p, char* smem) {
;     ...
;     for (int q = 0; q < 8; ++q) {
;       int tl = w * 8 + q;
;       float v0 = hs[tl * 132 + lane], v1 = hs[tl * 132 + 64 + lane];
;       float ss = wave_sum(v0 * v0 + v1 * v1);
;       float rstd = rsqrtf(ss * (1.0f / 128.0f) + 1e-6f);
;       int row = rowbase + c * 64 + tl;
;       const bf16_t* po = p.ACT() + (size_t)row * PW + 2208 + h * 128;
;       float o0 = bf2f(po[lane]), o1 = bf2f(po[64 + lane]);
;       float y0 = v0 * rstd * p.mlstm_out_g[h * 128 + lane] * sigmoidf_(o0);
;       float y1 = v1 * rstd * p.mlstm_out_g[h * 128 + 64 + lane] * sigmoidf_(o1);
;       MIX[(size_t)row * D + 512 + h * 128 + lane] = f2bf(y0);
;       MIX[(size_t)row * D + 512 + h * 128 + 64 + lane] = f2bf(y1);
	v_pk_add_f32 v[10:11], v[10:11], v[16:17]
	s_nop 0
	v_pk_fma_f32 v[10:11], v[10:11], s[16:17], v[4:5] op_sel_hi:[1,0,0]
	s_nop 0
	v_mul_f32_e32 v16, 0x4b800000, v11
	v_cmp_gt_f32_e64 s[78:79], s12, v11
	v_cmp_gt_f32_e32 vcc, s12, v10
	s_nop 0
	v_cndmask_b32_e64 v11, v11, v16, s[78:79]
	v_rsq_f32_e32 v11, v11
	s_nop 0
	v_mul_f32_e32 v16, 0x45800000, v11
	v_cndmask_b32_e64 v11, v11, v16, s[78:79]
	v_mul_f32_e32 v8, v8, v11
	v_mul_f32_e32 v8, v13, v8
	v_mul_f32_e32 v3, v3, v8
	v_mul_f32_e32 v8, v9, v11
	v_mul_f32_e32 v8, v12, v8
	v_bfe_u32 v9, v3, 16, 1
	v_mul_f32_e32 v8, v20, v8
	v_add3_u32 v3, v3, v9, s28
	global_store_short_d16_hi v[14:15], v3, off offset:1024
	v_bfe_u32 v3, v8, 16, 1
	v_add3_u32 v3, v8, v3, s28
	global_store_short_d16_hi v[14:15], v3, off offset:1152
	v_mul_f32_e32 v3, 0x4b800000, v10
	v_cndmask_b32_e32 v3, v10, v3, vcc
	v_rsq_f32_e32 v3, v3
	s_nop 0
	v_mul_f32_e32 v8, 0x45800000, v3
	v_cndmask_b32_e32 v3, v3, v8, vcc
	v_add_u32_e32 v8, 3, v2
	v_mad_i64_i32 v[10:11], s[2:3], v8, s13, v[0:1]
	v_lshl_add_u64 v[10:11], v[10:11], 0, s[30:31]
	v_lshl_add_u64 v[10:11], v[10:11], 0, v[166:167]
	v_lshl_add_u64 v[14:15], v[10:11], 0, s[14:15]
	v_add_co_u32_e32 v10, vcc, s11, v10
	v_mul_f32_e32 v6, v6, v3
	s_nop 0
	v_addc_co_u32_e32 v11, vcc, 0, v11, vcc
	v_mov_b32_e32 v10, v186
	v_mul_f32_e32 v3, v7, v3
	v_mov_b32_e32 v11, v187
	v_mul_f32_e32 v6, v13, v6
	v_mul_f32_e32 v3, v12, v3
	v_ashrrev_i32_e32 v9, 31, v8
	v_lshlrev_b32_e32 v10, 16, v10
	v_mul_f32_e32 v10, 0xbfb8aa3b, v10
	v_lshlrev_b32_e32 v11, 16, v11
	v_exp_f32_e32 v10, v10
	v_mul_f32_e32 v7, 0xbfb8aa3b, v11
	v_exp_f32_e32 v7, v7
	v_add_f32_e32 v10, 1.0, v10
	v_rcp_f32_e32 v10, v10
	v_add_f32_e32 v7, 1.0, v7
	v_rcp_f32_e32 v7, v7
	v_mul_f32_e32 v6, v10, v6
	v_mul_f32_e32 v3, v7, v3
	v_bfe_u32 v7, v6, 16, 1
	v_add3_u32 v10, v6, v7, s28
	v_lshlrev_b64 v[6:7], 11, v[8:9]
	v_lshl_add_u64 v[6:7], s[94:95], 0, v[6:7]
	v_lshl_add_u64 v[6:7], v[6:7], 0, v[166:167]
	global_store_short_d16_hi v[6:7], v10, off offset:1024
	v_add_u32_e32 v10, 4, v2
	v_mad_i64_i32 v[14:15], s[2:3], v10, s13, v[0:1]
	v_lshl_add_u64 v[14:15], v[14:15], 0, s[30:31]
	v_bfe_u32 v8, v3, 16, 1
	v_lshl_add_u64 v[14:15], v[14:15], 0, v[166:167]
	v_add3_u32 v3, v3, v8, s28
	v_lshl_add_u64 v[16:17], v[14:15], 0, s[14:15]
	v_add_co_u32_e32 v14, vcc, s11, v14
	global_store_short_d16_hi v[6:7], v3, off offset:1152
	s_nop 0
	v_addc_co_u32_e32 v15, vcc, 0, v15, vcc
	ds_read_b32 v6, v129
	ds_read_b32 v7, v130 offset:256
	v_mov_b32_e32 v3, v188
	v_ashrrev_i32_e32 v11, 31, v10
	v_mov_b32_e32 v14, v189
	v_lshlrev_b64 v[10:11], 11, v[10:11]
	v_lshl_add_u64 v[10:11], s[94:95], 0, v[10:11]
	s_waitcnt lgkmcnt(0)
	v_pk_mul_f32 v[8:9], v[6:7], v[6:7]
	v_lshlrev_b32_e32 v3, 16, v3
	v_mov_b32_e32 v19, v8
	v_lshlrev_b32_e32 v14, 16, v14
	v_mul_f32_e32 v14, 0xbfb8aa3b, v14
	v_exp_f32_e32 v14, v14
	v_mul_f32_e32 v3, 0xbfb8aa3b, v3
	v_exp_f32_e32 v3, v3
	v_add_f32_e32 v14, 1.0, v14
	v_rcp_f32_e32 v20, v14
	v_lshl_add_u64 v[14:15], v[10:11], 0, v[166:167]
	ds_read_b32 v10, v131
	ds_read_b32 v11, v132 offset:256
	v_add_f32_e32 v3, 1.0, v3
	v_rcp_f32_e32 v3, v3
	s_waitcnt lgkmcnt(0)
	v_pk_mul_f32 v[16:17], v[10:11], v[10:11]
	s_nop 0
	v_mov_b32_e32 v18, v16
	v_mov_b32_e32 v8, v17
	v_pk_add_f32 v[8:9], v[18:19], v[8:9]
	ds_bpermute_b32 v17, v67, v9
	ds_bpermute_b32 v16, v67, v8
	s_waitcnt lgkmcnt(0)
	v_pk_add_f32 v[8:9], v[8:9], v[16:17]
	ds_bpermute_b32 v17, v68, v9
	ds_bpermute_b32 v16, v68, v8
	s_waitcnt lgkmcnt(0)
	v_pk_add_f32 v[8:9], v[8:9], v[16:17]
	ds_bpermute_b32 v17, v56, v9
	ds_bpermute_b32 v16, v56, v8
	s_waitcnt lgkmcnt(0)
	v_pk_add_f32 v[8:9], v[8:9], v[16:17]
	ds_bpermute_b32 v17, v55, v9
	ds_bpermute_b32 v16, v55, v8
	s_waitcnt lgkmcnt(0)
	v_pk_add_f32 v[8:9], v[8:9], v[16:17]
	ds_bpermute_b32 v17, v54, v9
	ds_bpermute_b32 v16, v54, v8
	s_waitcnt lgkmcnt(0)
	v_pk_add_f32 v[8:9], v[8:9], v[16:17]
	ds_bpermute_b32 v17, v53, v9
	ds_bpermute_b32 v16, v53, v8
	s_waitcnt lgkmcnt(0)
;   __host__ __device__ __forceinline__ bf16_t* ACT() const { return (bf16_t*)(wsl() + OFF_ACT); }
; __device__ __forceinline__ float bf2f(bf16_t h) { return __uint_as_float(((uint32_t)h) << 16); }
; __device__ __forceinline__ float sigmoidf_(float x) { return __builtin_amdgcn_rcpf(1.0f + __expf(-x)); }
; __device__ __forceinline__ void m3_phase(const Params& p, char* smem) {
;     ...
;     for (int q = 0; q < 8; ++q) {
;       int tl = w * 8 + q;
;       float v0 = hs[tl * 132 + lane], v1 = hs[tl * 132 + 64 + lane];
;       float ss = wave_sum(v0 * v0 + v1 * v1);
;       float rstd = rsqrtf(ss * (1.0f / 128.0f) + 1e-6f);
;       int row = rowbase + c * 64 + tl;
;       const bf16_t* po = p.ACT() + (size_t)row * PW + 2208 + h * 128;
;       float o0 = bf2f(po[lane]), o1 = bf2f(po[64 + lane]);
;       float y0 = v0 * rstd * p.mlstm_out_g[h * 128 + lane] * sigmoidf_(o0);
;       float y1 = v1 * rstd * p.mlstm_out_g[h * 128 + 64 + lane] * sigmoidf_(o1);
;       MIX[(size_t)row * D + 512 + h * 128 + lane] = f2bf(y0);
;       MIX[(size_t)row * D + 512 + h * 128 + 64 + lane] = f2bf(y1);
;     }
;     __syncthreads();
	v_pk_add_f32 v[8:9], v[8:9], v[16:17]
	s_nop 0
	v_pk_fma_f32 v[8:9], v[8:9], s[16:17], v[4:5] op_sel_hi:[1,0,0]
	s_nop 0
	v_mul_f32_e32 v16, 0x4b800000, v9
	v_cmp_gt_f32_e64 s[78:79], s12, v9
	v_cmp_gt_f32_e32 vcc, s12, v8
	s_nop 0
	v_cndmask_b32_e64 v9, v9, v16, s[78:79]
	v_rsq_f32_e32 v9, v9
	s_nop 0
	v_mul_f32_e32 v16, 0x45800000, v9
	v_cndmask_b32_e64 v9, v9, v16, s[78:79]
	v_mul_f32_e32 v6, v6, v9
	v_mul_f32_e32 v6, v13, v6
	v_mul_f32_e32 v3, v3, v6
	v_mul_f32_e32 v6, v7, v9
	v_mul_f32_e32 v6, v12, v6
	v_bfe_u32 v7, v3, 16, 1
	v_mul_f32_e32 v6, v20, v6
	v_add3_u32 v3, v3, v7, s28
	global_store_short_d16_hi v[14:15], v3, off offset:1024
	v_bfe_u32 v3, v6, 16, 1
	v_add3_u32 v3, v6, v3, s28
	global_store_short_d16_hi v[14:15], v3, off offset:1152
	v_mul_f32_e32 v3, 0x4b800000, v8
	v_cndmask_b32_e32 v3, v8, v3, vcc
	v_rsq_f32_e32 v3, v3
	s_nop 0
	v_mul_f32_e32 v6, 0x45800000, v3
	v_cndmask_b32_e32 v3, v3, v6, vcc
	v_add_u32_e32 v6, 5, v2
	v_mad_i64_i32 v[8:9], s[2:3], v6, s13, v[0:1]
	v_lshl_add_u64 v[8:9], v[8:9], 0, s[30:31]
	v_lshl_add_u64 v[8:9], v[8:9], 0, v[166:167]
	v_lshl_add_u64 v[14:15], v[8:9], 0, s[14:15]
	v_add_co_u32_e32 v8, vcc, s11, v8
	v_mul_f32_e32 v10, v10, v3
	s_nop 0
	v_addc_co_u32_e32 v9, vcc, 0, v9, vcc
	v_mov_b32_e32 v8, v190
	v_ashrrev_i32_e32 v7, 31, v6
	v_mov_b32_e32 v9, v191
	v_mul_f32_e32 v10, v13, v10
	v_mul_f32_e32 v3, v11, v3
	v_mul_f32_e32 v3, v12, v3
	v_lshlrev_b64 v[6:7], 11, v[6:7]
	v_lshl_add_u64 v[6:7], s[94:95], 0, v[6:7]
	v_lshl_add_u64 v[6:7], v[6:7], 0, v[166:167]
	v_lshlrev_b32_e32 v8, 16, v8
	v_mul_f32_e32 v8, 0xbfb8aa3b, v8
	v_lshlrev_b32_e32 v9, 16, v9
	v_exp_f32_e32 v8, v8
	v_mul_f32_e32 v9, 0xbfb8aa3b, v9
	v_exp_f32_e32 v9, v9
	v_add_f32_e32 v8, 1.0, v8
	v_rcp_f32_e32 v8, v8
	v_add_f32_e32 v9, 1.0, v9
	v_rcp_f32_e32 v9, v9
	v_mul_f32_e32 v8, v8, v10
	v_mul_f32_e32 v3, v9, v3
	v_bfe_u32 v9, v8, 16, 1
	v_add3_u32 v8, v8, v9, s28
	global_store_short_d16_hi v[6:7], v8, off offset:1024
	v_bfe_u32 v8, v3, 16, 1
	v_add3_u32 v3, v3, v8, s28
	global_store_short_d16_hi v[6:7], v3, off offset:1152
	v_add_u32_e32 v6, 6, v2
	v_mad_i64_i32 v[14:15], s[2:3], v6, s13, v[0:1]
	v_lshl_add_u64 v[14:15], v[14:15], 0, s[30:31]
	v_lshl_add_u64 v[14:15], v[14:15], 0, v[166:167]
	v_lshl_add_u64 v[16:17], v[14:15], 0, s[14:15]
	v_add_co_u32_e32 v14, vcc, s11, v14
	ds_read_b32 v8, v133
	ds_read_b32 v9, v134 offset:256
	v_addc_co_u32_e32 v15, vcc, 0, v15, vcc
	v_mov_b32_e32 v3, v192
	v_ashrrev_i32_e32 v7, 31, v6
	v_mov_b32_e32 v14, v193
	v_lshlrev_b64 v[6:7], 11, v[6:7]
	v_lshl_add_u64 v[6:7], s[94:95], 0, v[6:7]
	s_waitcnt lgkmcnt(0)
	v_pk_mul_f32 v[10:11], v[8:9], v[8:9]
	v_add_u32_e32 v2, 7, v2
	v_mov_b32_e32 v19, v10
	v_mad_i64_i32 v[0:1], s[2:3], v2, s13, v[0:1]
	v_lshl_add_u64 v[0:1], v[0:1], 0, s[30:31]
	v_lshl_add_u64 v[0:1], v[0:1], 0, v[166:167]
	v_readlane_b32 s2, v255, 28
	v_lshlrev_b32_e32 v3, 16, v3
	v_mul_f32_e32 v3, 0xbfb8aa3b, v3
	v_lshlrev_b32_e32 v14, 16, v14
	v_mul_f32_e32 v14, 0xbfb8aa3b, v14
	v_exp_f32_e32 v14, v14
	v_exp_f32_e32 v3, v3
	v_add_u32_e32 v145, s2, v145
	v_add_u32_e32 v66, s2, v66
	v_add_f32_e32 v14, 1.0, v14
	v_rcp_f32_e32 v20, v14
	v_lshl_add_u64 v[14:15], v[6:7], 0, v[166:167]
	ds_read_b32 v6, v135
	ds_read_b32 v7, v136 offset:256
	v_add_f32_e32 v3, 1.0, v3
	v_rcp_f32_e32 v3, v3
	v_add_u32_e32 v144, s2, v144
	s_waitcnt lgkmcnt(0)
	v_pk_mul_f32 v[16:17], v[6:7], v[6:7]
	s_nop 0
	v_mov_b32_e32 v18, v16
	v_mov_b32_e32 v10, v17
	v_pk_add_f32 v[10:11], v[18:19], v[10:11]
	ds_bpermute_b32 v17, v67, v11
	ds_bpermute_b32 v16, v67, v10
	s_waitcnt lgkmcnt(0)
	v_pk_add_f32 v[10:11], v[10:11], v[16:17]
	ds_bpermute_b32 v17, v68, v11
	ds_bpermute_b32 v16, v68, v10
	s_waitcnt lgkmcnt(0)
	v_pk_add_f32 v[10:11], v[10:11], v[16:17]
	ds_bpermute_b32 v17, v56, v11
	ds_bpermute_b32 v16, v56, v10
	s_waitcnt lgkmcnt(0)
	v_pk_add_f32 v[10:11], v[10:11], v[16:17]
	ds_bpermute_b32 v17, v55, v11
	ds_bpermute_b32 v16, v55, v10
	s_waitcnt lgkmcnt(0)
	v_pk_add_f32 v[10:11], v[10:11], v[16:17]
	ds_bpermute_b32 v17, v54, v11
	ds_bpermute_b32 v16, v54, v10
	s_waitcnt lgkmcnt(0)
	v_pk_add_f32 v[10:11], v[10:11], v[16:17]
	ds_bpermute_b32 v17, v53, v11
	ds_bpermute_b32 v16, v53, v10
	s_waitcnt lgkmcnt(0)
	v_pk_add_f32 v[10:11], v[10:11], v[16:17]
	s_nop 0
	v_pk_fma_f32 v[4:5], v[10:11], s[16:17], v[4:5] op_sel_hi:[1,0,0]
	s_nop 0
	v_mul_f32_e32 v10, 0x4b800000, v5
	v_cmp_gt_f32_e64 s[78:79], s12, v5
	v_cmp_gt_f32_e32 vcc, s12, v4
	s_nop 0
	v_cndmask_b32_e64 v5, v5, v10, s[78:79]
	v_rsq_f32_e32 v5, v5
	s_nop 0
	v_mul_f32_e32 v10, 0x45800000, v5
	v_cndmask_b32_e64 v5, v5, v10, s[78:79]
	v_mul_f32_e32 v8, v8, v5
	v_mul_f32_e32 v8, v13, v8
	v_mul_f32_e32 v3, v3, v8
	v_mul_f32_e32 v5, v9, v5
	v_mul_f32_e32 v5, v12, v5
	v_bfe_u32 v8, v3, 16, 1
	v_mul_f32_e32 v5, v20, v5
	v_add3_u32 v3, v3, v8, s28
	global_store_short_d16_hi v[14:15], v3, off offset:1024
	v_bfe_u32 v3, v5, 16, 1
	v_add3_u32 v3, v5, v3, s28
	global_store_short_d16_hi v[14:15], v3, off offset:1152
	v_mul_f32_e32 v3, 0x4b800000, v4
	v_cndmask_b32_e32 v3, v4, v3, vcc
	v_rsq_f32_e32 v3, v3
	v_lshl_add_u64 v[8:9], v[0:1], 0, s[14:15]
	v_mul_f32_e32 v4, 0x45800000, v3
	v_cndmask_b32_e32 v4, v3, v4, vcc
	v_add_co_u32_e32 v0, vcc, s11, v0
	v_mul_f32_e32 v5, v6, v4
	s_nop 0
	v_addc_co_u32_e32 v1, vcc, 0, v1, vcc
	v_mov_b32_e32 v0, v194
	v_mul_f32_e32 v5, v13, v5
	v_mov_b32_e32 v1, v195
	v_mul_f32_e32 v4, v7, v4
	v_mul_f32_e32 v4, v12, v4
	v_ashrrev_i32_e32 v3, 31, v2
	v_lshlrev_b32_e32 v0, 16, v0
	v_mul_f32_e32 v0, 0xbfb8aa3b, v0
	v_lshlrev_b32_e32 v1, 16, v1
	v_exp_f32_e32 v0, v0
	v_mul_f32_e32 v1, 0xbfb8aa3b, v1
	v_exp_f32_e32 v1, v1
	v_add_f32_e32 v0, 1.0, v0
	v_rcp_f32_e32 v0, v0
	v_add_f32_e32 v1, 1.0, v1
	v_rcp_f32_e32 v1, v1
	v_mul_f32_e32 v0, v0, v5
	v_mul_f32_e32 v4, v1, v4
	v_bfe_u32 v1, v0, 16, 1
	v_add3_u32 v5, v0, v1, s28
	v_lshlrev_b64 v[0:1], 11, v[2:3]
	v_lshl_add_u64 v[0:1], s[94:95], 0, v[0:1]
	v_bfe_u32 v2, v4, 16, 1
	v_lshl_add_u64 v[0:1], v[0:1], 0, v[166:167]
	v_add3_u32 v2, v4, v2, s28
	global_store_short_d16_hi v[0:1], v5, off offset:1024
	global_store_short_d16_hi v[0:1], v2, off offset:1152
	s_barrier
	s_cbranch_scc1 .LBB0_549

;   __host__ __device__ __forceinline__ bf16_t* ACT() const { return (bf16_t*)(wsl() + OFF_ACT); }
;   __host__ __device__ __forceinline__ bf16_t* R() const { return (bf16_t*)(wsl() + OFF_R); }
; #define MFMA16(a, b, c) __builtin_amdgcn_mfma_f32_16x16x32_bf16(a, b, c, 0, 0, 0)
; __device__ __forceinline__ void m3_phase(const Params& p, char* smem) {
;     ...
; #pragma unroll
;       for (int i = 0; i < 2; ++i) {
;         int idx = tid + i * NTHR;
;         int r = idx & 63, fc = (idx >> 6) * 8;
;         int row = rowbase + mchunk_tok(dir, j, r);
;         const bf16_t* src = p.ACT() + (size_t)row * PW;
;         uint4 qv = *(const uint4*)(src + 672 + h * 128 + fc);
;         uint4 kv = *(const uint4*)(src + 1184 + h * 128 + fc);
;         uint4 vv = *(const uint4*)(src + 1696 + h * 128 + fc);
;         *(uint4*)(Qs + r * 136 + fc) = qv;
;         *(uint4*)(Ks + r * 136 + fc) = kv;
;         const bf16_t* ve = (const bf16_t*)&vv;
; #pragma unroll
;         for (int e = 0; e < 8; ++e) Vt[(fc + e) * 72 + r] = ve[e];
;       }
;       {
;         const bf16_t* cst = p.R() + (size_t)sidx * 16384;
; #pragma unroll
;         for (int i = 0; i < 4; ++i) {
;           int idx = tid + i * NTHR;
;           int v = idx >> 4, kc = (idx & 15) * 8;
;           *(uint4*)(Cs + v * 136 + kc) = *(const uint4*)(cst + v * 128 + kc);
;         }
;       }
;       __syncthreads();
;       {
;         const int mi = w & 3, nb2 = (w >> 2) * 2;
;         f32x4 s2[2] = {(f32x4){0.f, 0.f, 0.f, 0.f}, (f32x4){0.f, 0.f, 0.f, 0.f}};
; #pragma unroll
;         for (int ks = 0; ks < 4; ++ks) {
;           bf16x8 a = *(const bf16x8*)(Qs + (mi * 16 + fr) * 136 + ks * 32 + fq * 8);
; #pragma unroll
;           for (int q = 0; q < 2; ++q) {
;             bf16x8 bb = *(const bf16x8*)(Ks + ((nb2 + q) * 16 + fr) * 136 + ks * 32 + fq * 8);
;             s2[q] = MFMA16(a, bb, s2[q]);
;           }
;         }
.LBB0_491:
	s_or_b64 exec, exec, s[2:3]
	s_sub_i32 s11, s12, s11
	s_add_i32 s11, s11, s9
	v_add_u32_e32 v4, s11, v144
	v_mov_b64_e32 v[2:3], s[90:91]
	v_mad_i64_i32 v[2:3], s[2:3], v4, s84, v[2:3]
	s_lshl_b32 s30, s13, 8
	v_lshl_add_u64 v[14:15], v[2:3], 0, s[30:31]
	v_lshl_add_u64 v[10:11], v[36:37], 1, v[14:15]
	global_load_dwordx4 v[2:5], v[10:11], off offset:1344
	global_load_dwordx4 v[6:9], v[10:11], off offset:2368
	s_nop 0
	global_load_dwordx4 v[10:13], v[10:11], off offset:3392
	v_lshlrev_b64 v[0:1], 15, v[0:1]
	s_waitcnt vmcnt(2)
	ds_write_b128 v76, v[2:5]
	s_waitcnt vmcnt(1)
	ds_write_b128 v76, v[6:9] offset:17408
	s_waitcnt vmcnt(0)
	ds_write_b16 v33, v10 offset:34816
	ds_write_b16_d16_hi v33, v10 offset:34960
	ds_write_b16 v33, v11 offset:35104
	ds_write_b16_d16_hi v33, v11 offset:35248
	ds_write_b16 v33, v12 offset:35392
	ds_write_b16_d16_hi v33, v12 offset:35536
	ds_write_b16 v33, v13 offset:35680
	ds_write_b16_d16_hi v137, v13 offset:34816
	v_lshl_add_u64 v[10:11], v[38:39], 1, v[14:15]
	global_load_dwordx4 v[2:5], v[10:11], off offset:1344
	global_load_dwordx4 v[6:9], v[10:11], off offset:2368
	s_nop 0
	global_load_dwordx4 v[10:13], v[10:11], off offset:3392
	s_waitcnt vmcnt(2)
	ds_write_b128 v77, v[2:5]
	s_waitcnt vmcnt(1)
	ds_write_b128 v77, v[6:9] offset:17408
	s_waitcnt vmcnt(0)
	ds_write_b16 v138, v10 offset:34816
	ds_write_b16_d16_hi v138, v10 offset:34960
	ds_write_b16 v138, v11 offset:35104
	ds_write_b16_d16_hi v138, v11 offset:35248
	ds_write_b16 v138, v12 offset:35392
	ds_write_b16_d16_hi v138, v12 offset:35536
	ds_write_b16 v138, v13 offset:35680
	ds_write_b16_d16_hi v139, v13 offset:34816
	v_lshl_add_u64 v[4:5], v[48:49], 0, v[0:1]
	v_lshl_add_u64 v[0:1], v[40:41], 1, v[4:5]
	global_load_dwordx4 v[0:3], v[0:1], off
	s_waitcnt vmcnt(0)
	ds_write_b128 v78, v[0:3]
	v_lshl_add_u64 v[0:1], v[42:43], 1, v[4:5]
	global_load_dwordx4 v[0:3], v[0:1], off
	s_waitcnt vmcnt(0)
	ds_write_b128 v79, v[0:3]
	v_lshl_add_u64 v[0:1], v[44:45], 1, v[4:5]
	global_load_dwordx4 v[0:3], v[0:1], off
	s_waitcnt vmcnt(0)
	ds_write_b128 v80, v[0:3]
	v_lshl_add_u64 v[0:1], v[46:47], 1, v[4:5]
	global_load_dwordx4 v[0:3], v[0:1], off
	s_waitcnt vmcnt(0)
	ds_write_b128 v81, v[0:3]
	s_waitcnt lgkmcnt(0)
	s_barrier
	ds_read_b128 v[160:163], v52
	ds_read_b128 v[172:175], v140 offset:17408
	ds_read_b128 v[196:199], v140 offset:21760
	ds_read_b128 v[200:203], v52 offset:64
	ds_read_b128 v[204:207], v140 offset:17472
	ds_read_b128 v[208:211], v140 offset:21824
	ds_read_b128 v[212:215], v52 offset:128
	ds_read_b128 v[236:239], v140 offset:17536
	ds_read_b128 v[240:243], v140 offset:21888
	ds_read_b128 v[244:247], v52 offset:192
	s_waitcnt lgkmcnt(8)
	v_mfma_f32_16x16x32_bf16 v[4:7], v[160:163], v[172:175], 0
	ds_read_b128 v[248:251], v140 offset:17600
	s_waitcnt lgkmcnt(8)
	v_mfma_f32_16x16x32_bf16 v[0:3], v[160:163], v[196:199], 0
	ds_read_b128 v[172:175], v140 offset:21952
	s_waitcnt lgkmcnt(7)
	v_mfma_f32_16x16x32_bf16 v[4:7], v[200:203], v[204:207], v[4:7]
	s_waitcnt lgkmcnt(6)
	v_mfma_f32_16x16x32_bf16 v[0:3], v[200:203], v[208:211], v[0:3]
	s_waitcnt lgkmcnt(4)
	v_mfma_f32_16x16x32_bf16 v[4:7], v[212:215], v[236:239], v[4:7]
	s_waitcnt lgkmcnt(3)
	v_mfma_f32_16x16x32_bf16 v[0:3], v[212:215], v[240:243], v[0:3]
	s_waitcnt lgkmcnt(1)
	v_mfma_f32_16x16x32_bf16 v[4:7], v[244:247], v[248:251], v[4:7]
	s_waitcnt lgkmcnt(0)
	v_mfma_f32_16x16x32_bf16 v[0:3], v[244:247], v[172:175], v[0:3]
	ds_read_b32 v10, v82
	v_mov_b32_e32 v11, 0
	v_mov_b32_e32 v8, 0
	s_and_saveexec_b64 s[2:3], s[60:61]
	s_cbranch_execz .LBB0_493
	ds_read_b32 v8, v84
	s_waitcnt lgkmcnt(0)
	v_add_f32_e32 v8, v10, v8
	v_mul_f32_e32 v8, 0x3fb8aa3b, v8
	v_exp_f32_e32 v8, v8

; #define MFMA16(a, b, c) __builtin_amdgcn_mfma_f32_16x16x32_bf16(a, b, c, 0, 0, 0)
; __device__ __forceinline__ void m3_phase(const Params& p, char* smem) {
;     ...
;       {
;         const int mi = w & 3, nh = w >> 2;
;         f32x4 a1[4], a2[4];
; #pragma unroll
;         for (int q = 0; q < 4; ++q) { a1[q] = (f32x4){0.f, 0.f, 0.f, 0.f}; a2[q] = (f32x4){0.f, 0.f, 0.f, 0.f}; }
; #pragma unroll
;         for (int ks = 0; ks < 2; ++ks) {
;           bf16x8 a = *(const bf16x8*)(Sw + (mi * 16 + fr) * 72 + ks * 32 + fq * 8);
; #pragma unroll
;           for (int q = 0; q < 4; ++q) {
;             bf16x8 bb = *(const bf16x8*)(Vt + ((nh * 4 + q) * 16 + fr) * 72 + ks * 32 + fq * 8);
;             a1[q] = MFMA16(a, bb, a1[q]);
;           }
;         }
; #pragma unroll
;         for (int ks = 0; ks < 4; ++ks) {
;           bf16x8 a = *(const bf16x8*)(Qs + (mi * 16 + fr) * 136 + ks * 32 + fq * 8);
; #pragma unroll
;           for (int q = 0; q < 4; ++q) {
;             bf16x8 bb = *(const bf16x8*)(Cs + ((nh * 4 + q) * 16 + fr) * 136 + ks * 32 + fq * 8);
;             a2[q] = MFMA16(a, bb, a2[q]);
;           }
;         }
; #pragma unroll
;         for (int jj = 0; jj < 4; ++jj) {
;           int t = mi * 16 + fq * 4 + jj;
;           float wi = wint[t];
;           float den = denp[t] + denp[64 + t] + wi * qn[t];
;           float inv = 1.0f / fmaxf(fabsf(den), emt[t]);
;           int tl = (dir == 0) ? t : (63 - t);
; #pragma unroll
;           for (int q = 0; q < 4; ++q) {
;             int v = (nh * 4 + q) * 16 + fr;
;             float hv = (a1[q][jj] + wi * a2[q][jj]) * inv;
;             if (dir == 0) hs[tl * 132 + v] = hv; else hs[tl * 132 + v] += hv;
;           }
;         }
.LBB0_517:
	s_or_b64 exec, exec, s[2:3]
	s_waitcnt lgkmcnt(0)
	s_barrier
	v_add_u32_e32 v150, v35, v97
	s_mul_i32 s2, s15, 0xffffff7c
	s_add_i32 s2, s4, s2
	s_cmp_gt_i32 s2, 3
	s_cselect_b32 s16, 0x87, 3
	s_add_i32 s2, s16, s14
	s_add_i32 s2, s10, s2
	s_cmp_gt_i32 s2, 3
	s_mulk_i32 s15, 0x18c
	s_cselect_b32 s17, 0x87, 3
	ds_read_b128 v[160:163], v59
	ds_read_b128 v[172:175], v142 offset:34816
	ds_read_b128 v[196:199], v142 offset:37120
	ds_read_b128 v[200:203], v142 offset:39424
	ds_read_b128 v[204:207], v142 offset:41728
	ds_read_b128 v[208:211], v59 offset:64
	ds_read_b128 v[212:215], v142 offset:34880
	ds_read_b128 v[236:239], v150 offset:57600
	ds_read_b128 v[240:243], v150 offset:61952
	ds_read_b128 v[244:247], v142 offset:37184
	s_waitcnt lgkmcnt(6)
	v_mfma_f32_16x16x32_bf16 v[16:19], v[160:163], v[200:203], 0
	ds_read_b128 v[248:251], v143 offset:61952
	v_mfma_f32_16x16x32_bf16 v[4:7], v[160:163], v[172:175], 0
	ds_read_b128 v[200:203], v142 offset:39488
	v_mfma_f32_16x16x32_bf16 v[8:11], v[160:163], v[196:199], 0
	ds_read_b128 v[172:175], v142 offset:41792
	s_waitcnt lgkmcnt(8)
	v_mfma_f32_16x16x32_bf16 v[0:3], v[160:163], v[204:207], 0
	ds_read_b128 v[196:199], v52
	ds_read_b128 v[160:163], v150 offset:53248
	s_waitcnt lgkmcnt(8)
	v_mfma_f32_16x16x32_bf16 v[12:15], v[208:211], v[212:215], v[4:7]
	ds_read_b128 v[204:207], v52 offset:64
	s_waitcnt lgkmcnt(6)
	v_mfma_f32_16x16x32_bf16 v[8:11], v[208:211], v[244:247], v[8:11]
	ds_read_b128 v[212:215], v150 offset:53312
	s_waitcnt lgkmcnt(5)
	v_mfma_f32_16x16x32_bf16 v[4:7], v[208:211], v[200:203], v[16:19]
	ds_read_b128 v[244:247], v150 offset:57664
	s_waitcnt lgkmcnt(5)
	v_mfma_f32_16x16x32_bf16 v[0:3], v[208:211], v[172:175], v[0:3]
	ds_read_b128 v[200:203], v150 offset:62016
	ds_read_b128 v[208:211], v143 offset:62016
	s_waitcnt lgkmcnt(5)
	v_mfma_f32_16x16x32_bf16 v[20:23], v[196:199], v[160:163], 0
	ds_read_b128 v[172:175], v52 offset:128
	v_mfma_f32_16x16x32_bf16 v[24:27], v[196:199], v[236:239], 0
	ds_read_b128 v[160:163], v150 offset:53376
	v_mfma_f32_16x16x32_bf16 v[28:31], v[196:199], v[240:243], 0
	ds_read_b128 v[236:239], v150 offset:57728
	v_mfma_f32_16x16x32_bf16 v[16:19], v[196:199], v[248:251], 0
	ds_read_b128 v[240:243], v150 offset:62080
	ds_read_b128 v[196:199], v143 offset:62080
	s_waitcnt lgkmcnt(8)
	v_mfma_f32_16x16x32_bf16 v[20:23], v[204:207], v[212:215], v[20:23]
	ds_read_b128 v[248:251], v52 offset:192
	s_waitcnt lgkmcnt(8)
	v_mfma_f32_16x16x32_bf16 v[24:27], v[204:207], v[244:247], v[24:27]
	ds_read_b128 v[212:215], v150 offset:53440
	s_waitcnt lgkmcnt(8)
	v_mfma_f32_16x16x32_bf16 v[28:31], v[204:207], v[200:203], v[28:31]
	ds_read_b128 v[244:247], v150 offset:57792
	s_waitcnt lgkmcnt(8)
	v_mfma_f32_16x16x32_bf16 v[16:19], v[204:207], v[208:211], v[16:19]
	ds_read_b128 v[200:203], v150 offset:62144
	ds_read_b128 v[204:207], v143 offset:62144
	s_waitcnt lgkmcnt(8)
	v_mfma_f32_16x16x32_bf16 v[20:23], v[172:175], v[160:163], v[20:23]
	s_waitcnt lgkmcnt(7)
	v_mfma_f32_16x16x32_bf16 v[24:27], v[172:175], v[236:239], v[24:27]
	s_waitcnt lgkmcnt(6)
	v_mfma_f32_16x16x32_bf16 v[156:159], v[172:175], v[240:243], v[28:31]
	s_waitcnt lgkmcnt(5)
	v_mfma_f32_16x16x32_bf16 v[16:19], v[172:175], v[196:199], v[16:19]
	s_waitcnt lgkmcnt(3)
	v_mfma_f32_16x16x32_bf16 v[28:31], v[248:251], v[212:215], v[20:23]
	s_waitcnt lgkmcnt(2)
	v_mfma_f32_16x16x32_bf16 v[24:27], v[248:251], v[244:247], v[24:27]
	s_waitcnt lgkmcnt(1)
	v_mfma_f32_16x16x32_bf16 v[20:23], v[248:251], v[200:203], v[156:159]
	s_waitcnt lgkmcnt(0)
	v_mfma_f32_16x16x32_bf16 v[16:19], v[248:251], v[204:207], v[16:19]
	ds_read_b32 v151, v98
	ds_read2st64_b32 v[152:153], v99 offset1:1
	s_waitcnt lgkmcnt(1)
	v_fma_f32 v12, v28, v151, v12
	s_waitcnt lgkmcnt(0)
	v_add_f32_e32 v152, v152, v153
	ds_read_b32 v153, v100
	v_fma_f32 v8, v24, v151, v8
	v_fma_f32 v4, v20, v151, v4
	v_fma_f32 v0, v151, v16, v0
	s_waitcnt lgkmcnt(0)
	v_fmac_f32_e32 v152, v151, v153
	ds_read_b32 v153, v101
	s_waitcnt lgkmcnt(0)
	v_max_f32_e32 v153, v153, v153
	v_max_f32_e64 v152, |v152|, v153
	v_div_scale_f32 v153, s[2:3], v152, v152, 1.0
	v_rcp_f32_e32 v154, v153
	s_nop 0
	v_fma_f32 v155, -v153, v154, 1.0
	v_fmac_f32_e32 v154, v155, v154
	v_div_scale_f32 v155, vcc, 1.0, v152, 1.0
	v_mul_f32_e32 v156, v155, v154
	v_fma_f32 v157, -v153, v156, v155
	v_fmac_f32_e32 v156, v157, v154
	v_fma_f32 v153, -v153, v156, v155
	v_div_fmas_f32 v153, v153, v154, v156
	v_div_fixup_f32 v152, v153, v152, 1.0
	v_mul_f32_e32 v12, v12, v152
	v_mul_f32_e32 v8, v8, v152
	v_mul_f32_e32 v4, v4, v152
	v_mul_f32_e32 v0, v0, v152
	ds_write2_b32 v102, v12, v8 offset1:16
	ds_write2_b32 v102, v4, v0 offset0:32 offset1:48
	ds_read_b32 v0, v103
	ds_read_b32 v4, v104
	ds_read_b32 v8, v105
	ds_read2st64_b32 v[152:153], v106 offset1:1
	s_waitcnt lgkmcnt(3)
	v_fma_f32 v9, v25, v0, v9
	s_waitcnt lgkmcnt(2)
	v_max_f32_e32 v4, v4, v4
	v_fma_f32 v5, v21, v0, v5
	s_waitcnt lgkmcnt(0)
	v_add_f32_e32 v12, v153, v152
	v_fmac_f32_e32 v12, v0, v8
	v_max_f32_e64 v4, |v12|, v4
	v_div_scale_f32 v8, s[2:3], v4, v4, 1.0
	v_rcp_f32_e32 v12, v8
	s_nop 0
	v_fma_f32 v16, -v8, v12, 1.0
	v_fmac_f32_e32 v12, v16, v12
	v_div_scale_f32 v16, vcc, 1.0, v4, 1.0
	v_mul_f32_e32 v20, v16, v12
	v_fma_f32 v24, -v8, v20, v16
	v_fmac_f32_e32 v20, v24, v12
	v_fma_f32 v8, -v8, v20, v16
	v_div_fmas_f32 v8, v8, v12, v20
	v_div_fixup_f32 v4, v8, v4, 1.0
	v_fma_f32 v8, v29, v0, v13
	v_fma_f32 v0, v17, v0, v1
	v_mul_f32_e32 v8, v8, v4
	v_mul_f32_e32 v9, v9, v4
	v_mul_f32_e32 v5, v5, v4
	v_mul_f32_e32 v0, v0, v4
	ds_write2_b32 v107, v8, v9 offset1:16
	ds_write2_b32 v107, v5, v0 offset0:32 offset1:48
	ds_read_b32 v4, v108
	ds_read_b32 v5, v109
	ds_read_b32 v8, v110
	ds_read2st64_b32 v[0:1], v111 offset1:1
	s_waitcnt lgkmcnt(3)
; __device__ __forceinline__ void m3_phase(const Params& p, char* smem) {
;     ...
;       int ci = (b * 4 + h) * 2 + dir;
;       int j = (dir == 0) ? c : ((c < 4) ? (3 - c) : (135 - c));
;       int sidx = ci * NCHUNK + j;
;       if (w == 0) {
;         int row = rowbase + mchunk_tok(dir, j, lane);
;     ...
;         for (int jj = 0; jj < 4; ++jj) {
;           int t = mi * 16 + fq * 4 + jj;
;           float wi = wint[t];
;           float den = denp[t] + denp[64 + t] + wi * qn[t];
;           float inv = 1.0f / fmaxf(fabsf(den), emt[t]);
;           int tl = (dir == 0) ? t : (63 - t);
; #pragma unroll
;           for (int q = 0; q < 4; ++q) {
;             int v = (nh * 4 + q) * 16 + fr;
;             float hv = (a1[q][jj] + wi * a2[q][jj]) * inv;
;             if (dir == 0) hs[tl * 132 + v] = hv; else hs[tl * 132 + v] += hv;
;           }
;         }
;       }
;       __syncthreads();
	v_fma_f32 v2, v18, v4, v2
	s_waitcnt lgkmcnt(0)
	v_add_f32_e32 v0, v1, v0
	v_fmac_f32_e32 v0, v4, v8
	v_max_f32_e32 v1, v5, v5
	v_max_f32_e64 v0, |v0|, v1
	v_div_scale_f32 v1, s[2:3], v0, v0, 1.0
	v_rcp_f32_e32 v5, v1
	s_nop 0
	v_fma_f32 v8, -v1, v5, 1.0
	v_fmac_f32_e32 v5, v8, v5
	v_div_scale_f32 v8, vcc, 1.0, v0, 1.0
	v_mul_f32_e32 v9, v8, v5
	v_fma_f32 v12, -v1, v9, v8
	v_fmac_f32_e32 v9, v12, v5
	v_fma_f32 v1, -v1, v9, v8
	v_div_fmas_f32 v1, v1, v5, v9
	v_div_fixup_f32 v0, v1, v0, 1.0
	v_fma_f32 v1, v30, v4, v14
	v_fma_f32 v5, v26, v4, v10
	v_mul_f32_e32 v1, v1, v0
	v_mul_f32_e32 v5, v5, v0
	ds_write2_b32 v112, v1, v5 offset1:16
	v_fma_f32 v1, v22, v4, v6
	v_mul_f32_e32 v1, v1, v0
	v_mul_f32_e32 v0, v2, v0
	ds_write2_b32 v112, v1, v0 offset0:32 offset1:48
	ds_read_b32 v2, v113
	ds_read_b32 v4, v114
	ds_read_b32 v5, v115
	ds_read2st64_b32 v[0:1], v116 offset1:1
	s_waitcnt lgkmcnt(3)
	v_fmac_f32_e32 v15, v31, v2
	v_fmac_f32_e32 v11, v27, v2
	v_fmac_f32_e32 v7, v23, v2
	s_waitcnt lgkmcnt(0)
	v_add_f32_e32 v0, v1, v0
	v_fmac_f32_e32 v0, v2, v5
	v_max_f32_e32 v1, v4, v4
	v_max_f32_e64 v0, |v0|, v1
	v_div_scale_f32 v1, s[2:3], v0, v0, 1.0
	v_rcp_f32_e32 v4, v1
	s_add_i32 s2, s16, s15
	v_fmac_f32_e32 v3, v19, v2
	s_add_i32 s2, s10, s2
	v_fma_f32 v5, -v1, v4, 1.0
	v_fmac_f32_e32 v4, v5, v4
	v_div_scale_f32 v5, vcc, 1.0, v0, 1.0
	v_mul_f32_e32 v6, v5, v4
	v_fma_f32 v8, -v1, v6, v5
	v_fmac_f32_e32 v6, v8, v4
	v_fma_f32 v1, -v1, v6, v5
	v_div_fmas_f32 v1, v1, v4, v6
	v_div_fixup_f32 v0, v1, v0, 1.0
	v_mul_f32_e32 v1, v15, v0
	v_mul_f32_e32 v4, v11, v0
	ds_write2_b32 v117, v1, v4 offset1:16
	v_mul_f32_e32 v1, v7, v0
	v_mul_f32_e32 v0, v3, v0
	s_add_i32 s78, s2, 0x84
	ds_write2_b32 v117, v1, v0 offset0:32 offset1:48
	s_waitcnt lgkmcnt(0)
	s_barrier
	s_and_saveexec_b64 s[2:3], s[40:41]
	s_xor_b64 s[2:3], exec, s[2:3]
	s_ashr_i32 s79, s78, 31
	s_or_saveexec_b64 s[94:95], s[2:3]
	s_sub_i32 s2, s17, s16
	s_sub_i32 s2, s2, s14
	s_add_i32 s2, s4, s2
	s_lshl_b32 s14, s2, 6
	v_mov_b64_e32 v[0:1], s[78:79]
	s_xor_b64 exec, exec, s[94:95]
	s_cbranch_execz .LBB0_521
;   __host__ __device__ __forceinline__ float* G() const { return (float*)(wsl() + OFF_G); }
;   __host__ __device__ __forceinline__ float* mst() const { return (float*)(wsl() + OFF_MST); }
; __device__ __forceinline__ float logsigmoidf_(float x) { return fminf(x, 0.0f) - log1pf(__expf(-fabsf(x))); }
; __device__ __forceinline__ void m3_phase(const Params& p, char* smem) {
;     ...
;       if (w == 0) {
;         int row = rowbase + mchunk_tok(dir, j, lane);
;         float gi = p.G()[(size_t)row * 16 + (2 * dir) * 4 + h] + p.mlstm_gate_b[(2 * dir) * 4 + h];
;         float gf = p.G()[(size_t)row * 16 + (2 * dir + 1) * 4 + h] + p.mlstm_gate_b[(2 * dir + 1) * 4 + h];
;         float bsum = logsigmoidf_(gf);
; #pragma unroll
;         for (int o = 1; o < 64; o <<= 1) { float t = __shfl_up(bsum, o); if (lane >= o) bsum += t; }
;         float cv = gi - bsum;
;         float pm = cv;
; #pragma unroll
;         for (int o = 1; o < 64; o <<= 1) { float t = __shfl_up(pm, o); if (lane >= o) pm = fmaxf(pm, t); }
;         float mprev = p.mst()[sidx];
;         float mt = fmaxf(bsum + mprev, bsum + pm);
;         cs[lane] = cv;
;         rt[lane] = bsum - mt;
;         wint[lane] = __expf(bsum + mprev - mt);
;         emt[lane] = __expf(-mt);
;       }
	v_add_u32_e32 v0, s14, v32
	v_xad_u32 v0, v0, 63, s12
	s_load_dwordx2 s[2:3], s[0:1], 0x90
	v_ashrrev_i32_e32 v1, 31, v0
	v_lshlrev_b64 v[0:1], 6, v[0:1]
	v_lshl_add_u64 v[0:1], s[92:93], 0, v[0:1]
	s_lshl_b32 s30, s13, 2
	v_lshl_add_u64 v[0:1], v[0:1], 0, s[30:31]
	v_mov_b32_e32 v3, s30
	global_load_dword v2, v[0:1], off offset:32
	s_waitcnt lgkmcnt(0)
	global_load_dword v4, v3, s[2:3] offset:32
	s_nop 0
	global_load_dword v0, v[0:1], off offset:48
	s_nop 0
	global_load_dword v1, v3, s[2:3] offset:48
	s_mov_b32 s2, 0xbfb8aa3b
	s_ashr_i32 s79, s78, 31
	s_waitcnt vmcnt(0)
	v_add_f32_e32 v0, v0, v1
	v_min_f32_e32 v3, 0, v0
	v_mul_f32_e64 v0, |v0|, s2
	v_exp_f32_e32 v5, v0
	s_mov_b32 s2, 0x3f2aaaab
	v_add_f32_e32 v6, 1.0, v5
	v_add_f32_e32 v0, -1.0, v6
	v_sub_f32_e32 v1, v0, v6
	v_add_f32_e32 v1, 1.0, v1
	v_sub_f32_e32 v0, v5, v0
	v_add_f32_e32 v7, v0, v1
	v_frexp_mant_f32_e32 v0, v6
	v_cmp_gt_f32_e32 vcc, s2, v0
	v_cvt_f64_f32_e32 v[0:1], v6
	v_frexp_exp_i32_f64_e32 v0, v[0:1]
	v_subbrev_co_u32_e32 v0, vcc, 0, v0, vcc
	v_sub_u32_e32 v1, 0, v0
	v_ldexp_f32 v6, v6, v1
	v_ldexp_f32 v1, v7, v1
	v_add_f32_e32 v7, -1.0, v6
	v_add_f32_e32 v8, 1.0, v7
	v_sub_f32_e32 v8, v6, v8
	v_add_f32_e32 v8, v1, v8
	v_add_f32_e32 v9, v7, v8
	v_sub_f32_e32 v7, v9, v7
	v_sub_f32_e32 v7, v8, v7
	v_add_f32_e32 v8, 1.0, v6
	v_add_f32_e32 v10, -1.0, v8
	v_sub_f32_e32 v6, v6, v10
	v_add_f32_e32 v1, v1, v6
	v_add_f32_e32 v6, v8, v1
	v_sub_f32_e32 v8, v6, v8
	v_sub_f32_e32 v1, v1, v8
	v_rcp_f32_e32 v8, v6
	v_cvt_f32_i32_e32 v0, v0
	s_mov_b32 s2, 0x3f317218
	v_mul_f32_e32 v10, v9, v8
	v_mul_f32_e32 v11, v6, v10
	v_fma_f32 v12, v10, v6, -v11
	v_fmac_f32_e32 v12, v10, v1
	v_add_f32_e32 v13, v11, v12
	v_sub_f32_e32 v14, v9, v13
	v_sub_f32_e32 v9, v9, v14
	v_sub_f32_e32 v11, v13, v11
	v_sub_f32_e32 v9, v9, v13
	v_add_f32_e32 v7, v7, v9
	v_sub_f32_e32 v9, v11, v12
	v_add_f32_e32 v7, v9, v7
	v_add_f32_e32 v9, v14, v7
	v_mul_f32_e32 v11, v8, v9
	v_mul_f32_e32 v12, v6, v11
	v_fma_f32 v6, v11, v6, -v12
	v_fmac_f32_e32 v6, v11, v1
	v_sub_f32_e32 v1, v14, v9
	v_add_f32_e32 v1, v7, v1
	v_add_f32_e32 v7, v12, v6
	v_sub_f32_e32 v13, v9, v7
	v_sub_f32_e32 v9, v9, v13
	v_sub_f32_e32 v12, v7, v12
	v_sub_f32_e32 v7, v9, v7
	v_add_f32_e32 v1, v1, v7
	v_sub_f32_e32 v6, v12, v6
	v_add_f32_e32 v1, v6, v1
	v_add_f32_e32 v6, v10, v11
	v_add_f32_e32 v1, v13, v1
	v_sub_f32_e32 v7, v6, v10
	v_mul_f32_e32 v1, v8, v1
	v_sub_f32_e32 v7, v11, v7
	v_add_f32_e32 v1, v7, v1
	v_mul_f32_e32 v10, 0x3f317218, v0
	v_add_f32_e32 v7, v6, v1
	v_fma_f32 v11, v0, s2, -v10
	v_mul_f32_e32 v8, v7, v7
	v_fmac_f32_e32 v11, 0xb102e308, v0
	v_sub_f32_e32 v0, v7, v6
	v_fmamk_f32 v9, v8, 0x3e9b6dac, v165
	v_sub_f32_e32 v0, v1, v0
	v_add_f32_e32 v1, v10, v11
	v_fmaak_f32 v9, v8, v9, 0x3f2aaada
	v_sub_f32_e32 v6, v1, v10
	v_ldexp_f32 v10, v7, 1
	v_mul_f32_e32 v7, v7, v8
	v_mul_f32_e32 v7, v7, v9
	v_add_f32_e32 v8, v10, v7
	v_sub_f32_e32 v9, v8, v10
	v_ldexp_f32 v0, v0, 1
	v_sub_f32_e32 v7, v7, v9
	v_add_f32_e32 v0, v0, v7
	v_add_f32_e32 v7, v8, v0
	v_sub_f32_e32 v8, v7, v8
	v_sub_f32_e32 v0, v0, v8
	v_add_f32_e32 v8, v1, v7
	v_sub_f32_e32 v9, v8, v1
	v_sub_f32_e32 v10, v8, v9
	v_sub_f32_e32 v6, v11, v6
	v_sub_f32_e32 v1, v1, v10
	v_sub_f32_e32 v7, v7, v9
	v_add_f32_e32 v1, v7, v1
	v_add_f32_e32 v7, v6, v0
	v_sub_f32_e32 v9, v7, v6
	v_sub_f32_e32 v10, v7, v9
	v_sub_f32_e32 v6, v6, v10
	v_sub_f32_e32 v0, v0, v9
	v_add_f32_e32 v1, v7, v1
	v_add_f32_e32 v0, v0, v6
	v_add_f32_e32 v6, v8, v1
	v_sub_f32_e32 v7, v6, v8
	v_sub_f32_e32 v1, v1, v7
	v_add_f32_e32 v0, v0, v1
	s_mov_b32 s2, 0x7f800000
	v_add_f32_e32 v0, v6, v0
	v_cmp_neq_f32_e32 vcc, s2, v5
	s_mov_b32 s2, 0x33800000
	s_nop 0
	v_cndmask_b32_e32 v0, v225, v0, vcc
	v_cmp_ngt_f32_e32 vcc, -1.0, v5
	s_nop 1
	v_cndmask_b32_e32 v0, v226, v0, vcc
	v_cmp_neq_f32_e32 vcc, -1.0, v5
	s_nop 1
	v_cndmask_b32_e32 v0, v227, v0, vcc
	v_cmp_lt_f32_e64 vcc, |v5|, s2
	s_lshl_b64 s[2:3], s[78:79], 2
	s_add_u32 s2, s7, s2
	v_cndmask_b32_e32 v0, v0, v5, vcc
	v_sub_f32_e32 v0, v3, v0
	ds_bpermute_b32 v1, v70, v0
	s_addc_u32 s3, s8, s3
	s_waitcnt lgkmcnt(0)
	v_add_f32_e32 v1, v0, v1
	v_cndmask_b32_e64 v0, v1, v0, s[48:49]
	ds_bpermute_b32 v1, v71, v0
	s_waitcnt lgkmcnt(0)
	v_add_f32_e32 v1, v0, v1
	v_cndmask_b32_e64 v0, v1, v0, s[50:51]
	ds_bpermute_b32 v1, v72, v0
	s_waitcnt lgkmcnt(0)
	v_add_f32_e32 v1, v0, v1
	v_cndmask_b32_e64 v0, v1, v0, s[52:53]
	ds_bpermute_b32 v1, v73, v0
	s_waitcnt lgkmcnt(0)
	v_add_f32_e32 v1, v0, v1
	v_cndmask_b32_e64 v0, v1, v0, s[54:55]
	ds_bpermute_b32 v1, v74, v0
	s_waitcnt lgkmcnt(0)
	v_add_f32_e32 v1, v0, v1
	v_cndmask_b32_e64 v0, v1, v0, s[56:57]
	ds_bpermute_b32 v1, v75, v0
	s_waitcnt lgkmcnt(0)
	v_add_f32_e32 v1, v0, v1
	v_cndmask_b32_e64 v0, v1, v0, s[58:59]
	v_add_f32_e32 v1, v2, v4
	v_sub_f32_e32 v1, v1, v0
	ds_bpermute_b32 v2, v70, v1
	ds_write_b32 v60, v1
	s_waitcnt lgkmcnt(1)
	v_max_f32_e32 v2, v2, v2
	v_max_f32_e32 v2, v1, v2
	v_cndmask_b32_e64 v2, v2, v1, s[48:49]
	ds_bpermute_b32 v3, v71, v2
	s_waitcnt lgkmcnt(0)
	v_max_f32_e32 v3, v3, v3
	v_max_f32_e32 v3, v2, v3
	v_cndmask_b32_e64 v2, v3, v2, s[50:51]
	ds_bpermute_b32 v3, v72, v2
	s_waitcnt lgkmcnt(0)
	v_max_f32_e32 v3, v3, v3
	v_max_f32_e32 v3, v2, v3
	v_cndmask_b32_e64 v2, v3, v2, s[52:53]
	ds_bpermute_b32 v3, v73, v2
	s_waitcnt lgkmcnt(0)
	v_max_f32_e32 v3, v3, v3
	v_max_f32_e32 v3, v2, v3
	v_cndmask_b32_e64 v2, v3, v2, s[54:55]
	ds_bpermute_b32 v3, v74, v2
	s_waitcnt lgkmcnt(0)
	v_max_f32_e32 v3, v3, v3
	v_max_f32_e32 v3, v2, v3
	v_cndmask_b32_e64 v2, v3, v2, s[56:57]
	ds_bpermute_b32 v3, v75, v2
	v_max_f32_e32 v4, v2, v2
	s_waitcnt lgkmcnt(0)
	v_max_f32_e32 v3, v3, v3
	v_max_f32_e32 v3, v4, v3
	v_cndmask_b32_e64 v2, v3, v2, s[58:59]
	global_load_dword v3, v167, s[2:3]
	v_add_f32_e32 v2, v0, v2
	s_waitcnt vmcnt(0)
	v_add_f32_e32 v3, v3, v0
	v_max_f32_e32 v2, v3, v2
	v_sub_f32_e32 v0, v0, v2
	ds_write_b32 v61, v0
	v_sub_f32_e32 v0, v3, v2
	v_mul_f32_e32 v0, 0x3fb8aa3b, v0
	v_exp_f32_e32 v0, v0
	ds_write_b32 v62, v0
	v_mul_f32_e32 v0, 0xbfb8aa3b, v2
	v_exp_f32_e32 v0, v0
	ds_write_b32 v63, v0
	v_mov_b64_e32 v[0:1], s[78:79]

;   __host__ __device__ __forceinline__ bf16_t* ACT() const { return (bf16_t*)(wsl() + OFF_ACT); }
;   __host__ __device__ __forceinline__ bf16_t* R() const { return (bf16_t*)(wsl() + OFF_R); }
; #define MFMA16(a, b, c) __builtin_amdgcn_mfma_f32_16x16x32_bf16(a, b, c, 0, 0, 0)
; __device__ __forceinline__ void m3_phase(const Params& p, char* smem) {
;     ...
; #pragma unroll
;       for (int i = 0; i < 2; ++i) {
;         int idx = tid + i * NTHR;
;         int r = idx & 63, fc = (idx >> 6) * 8;
;         int row = rowbase + mchunk_tok(dir, j, r);
;         const bf16_t* src = p.ACT() + (size_t)row * PW;
;         uint4 qv = *(const uint4*)(src + 672 + h * 128 + fc);
;         uint4 kv = *(const uint4*)(src + 1184 + h * 128 + fc);
;         uint4 vv = *(const uint4*)(src + 1696 + h * 128 + fc);
;         *(uint4*)(Qs + r * 136 + fc) = qv;
;         *(uint4*)(Ks + r * 136 + fc) = kv;
;         const bf16_t* ve = (const bf16_t*)&vv;
; #pragma unroll
;         for (int e = 0; e < 8; ++e) Vt[(fc + e) * 72 + r] = ve[e];
;       }
;       {
;         const bf16_t* cst = p.R() + (size_t)sidx * 16384;
; #pragma unroll
;         for (int i = 0; i < 4; ++i) {
;           int idx = tid + i * NTHR;
;           int v = idx >> 4, kc = (idx & 15) * 8;
;           *(uint4*)(Cs + v * 136 + kc) = *(const uint4*)(cst + v * 128 + kc);
;         }
;       }
;       __syncthreads();
;       {
;         const int mi = w & 3, nb2 = (w >> 2) * 2;
;         f32x4 s2[2] = {(f32x4){0.f, 0.f, 0.f, 0.f}, (f32x4){0.f, 0.f, 0.f, 0.f}};
; #pragma unroll
;         for (int ks = 0; ks < 4; ++ks) {
;           bf16x8 a = *(const bf16x8*)(Qs + (mi * 16 + fr) * 136 + ks * 32 + fq * 8);
; #pragma unroll
;           for (int q = 0; q < 2; ++q) {
;             bf16x8 bb = *(const bf16x8*)(Ks + ((nb2 + q) * 16 + fr) * 136 + ks * 32 + fq * 8);
;             s2[q] = MFMA16(a, bb, s2[q]);
;           }
;         }
.LBB0_523:
	s_or_b64 exec, exec, s[2:3]
	v_or_b32_e32 v2, s14, v34
	s_lshl_b32 s13, s13, 7
	v_xad_u32 v4, v2, 63, s12
	v_mov_b64_e32 v[2:3], s[90:91]
	v_mad_i64_i32 v[2:3], s[2:3], v4, s84, v[2:3]
	s_lshl_b32 s30, s13, 1
	v_lshl_add_u64 v[14:15], v[2:3], 0, s[30:31]
	v_lshl_add_u64 v[10:11], v[36:37], 1, v[14:15]
	global_load_dwordx4 v[2:5], v[10:11], off offset:1344
	global_load_dwordx4 v[6:9], v[10:11], off offset:2368
	s_nop 0
	global_load_dwordx4 v[10:13], v[10:11], off offset:3392
	v_lshlrev_b64 v[0:1], 15, v[0:1]
	s_waitcnt vmcnt(2)
	ds_write_b128 v76, v[2:5]
	s_waitcnt vmcnt(1)
	ds_write_b128 v76, v[6:9] offset:17408
	s_waitcnt vmcnt(0)
	ds_write_b16 v33, v10 offset:34816
	ds_write_b16_d16_hi v33, v10 offset:34960
	ds_write_b16 v33, v11 offset:35104
	ds_write_b16_d16_hi v33, v11 offset:35248
	ds_write_b16 v33, v12 offset:35392
	ds_write_b16_d16_hi v33, v12 offset:35536
	ds_write_b16 v33, v13 offset:35680
	ds_write_b16_d16_hi v137, v13 offset:34816
	v_lshl_add_u64 v[10:11], v[38:39], 1, v[14:15]
	global_load_dwordx4 v[2:5], v[10:11], off offset:1344
	global_load_dwordx4 v[6:9], v[10:11], off offset:2368
	s_nop 0
	global_load_dwordx4 v[10:13], v[10:11], off offset:3392
	s_waitcnt vmcnt(2)
	ds_write_b128 v77, v[2:5]
	s_waitcnt vmcnt(1)
	ds_write_b128 v77, v[6:9] offset:17408
	s_waitcnt vmcnt(0)
	ds_write_b16 v138, v10 offset:34816
	ds_write_b16_d16_hi v138, v10 offset:34960
	ds_write_b16 v138, v11 offset:35104
	ds_write_b16_d16_hi v138, v11 offset:35248
	ds_write_b16 v138, v12 offset:35392
	ds_write_b16_d16_hi v138, v12 offset:35536
	ds_write_b16 v138, v13 offset:35680
	ds_write_b16_d16_hi v139, v13 offset:34816
	v_lshl_add_u64 v[4:5], v[48:49], 0, v[0:1]
	v_lshl_add_u64 v[0:1], v[40:41], 1, v[4:5]
	global_load_dwordx4 v[0:3], v[0:1], off
	s_waitcnt vmcnt(0)
	ds_write_b128 v78, v[0:3]
	v_lshl_add_u64 v[0:1], v[42:43], 1, v[4:5]
	global_load_dwordx4 v[0:3], v[0:1], off
	s_waitcnt vmcnt(0)
	ds_write_b128 v79, v[0:3]
	v_lshl_add_u64 v[0:1], v[44:45], 1, v[4:5]
	global_load_dwordx4 v[0:3], v[0:1], off
	s_waitcnt vmcnt(0)
	ds_write_b128 v80, v[0:3]
	v_lshl_add_u64 v[0:1], v[46:47], 1, v[4:5]
	global_load_dwordx4 v[0:3], v[0:1], off
	s_waitcnt vmcnt(0)
	ds_write_b128 v81, v[0:3]
	s_waitcnt lgkmcnt(0)
	s_barrier
	ds_read_b128 v[160:163], v52
	ds_read_b128 v[172:175], v140 offset:17408
	ds_read_b128 v[196:199], v140 offset:21760
	ds_read_b128 v[200:203], v52 offset:64
	ds_read_b128 v[204:207], v140 offset:17472
	ds_read_b128 v[208:211], v140 offset:21824
	ds_read_b128 v[212:215], v52 offset:128
	ds_read_b128 v[236:239], v140 offset:17536
	ds_read_b128 v[240:243], v140 offset:21888
	ds_read_b128 v[244:247], v52 offset:192
	s_waitcnt lgkmcnt(8)
	v_mfma_f32_16x16x32_bf16 v[4:7], v[160:163], v[172:175], 0
	ds_read_b128 v[248:251], v140 offset:17600
	s_waitcnt lgkmcnt(8)
	v_mfma_f32_16x16x32_bf16 v[0:3], v[160:163], v[196:199], 0
	ds_read_b128 v[172:175], v140 offset:21952
	s_waitcnt lgkmcnt(7)
	v_mfma_f32_16x16x32_bf16 v[4:7], v[200:203], v[204:207], v[4:7]
	s_waitcnt lgkmcnt(6)
	v_mfma_f32_16x16x32_bf16 v[0:3], v[200:203], v[208:211], v[0:3]
	s_waitcnt lgkmcnt(4)
	v_mfma_f32_16x16x32_bf16 v[4:7], v[212:215], v[236:239], v[4:7]
	s_waitcnt lgkmcnt(3)
	v_mfma_f32_16x16x32_bf16 v[0:3], v[212:215], v[240:243], v[0:3]
	s_waitcnt lgkmcnt(1)
	v_mfma_f32_16x16x32_bf16 v[4:7], v[244:247], v[248:251], v[4:7]
	s_waitcnt lgkmcnt(0)
	v_mfma_f32_16x16x32_bf16 v[0:3], v[244:247], v[172:175], v[0:3]
	ds_read_b32 v10, v82
	v_mov_b32_e32 v11, 0
	v_mov_b32_e32 v8, 0
	s_and_saveexec_b64 s[2:3], s[60:61]
	s_cbranch_execz .LBB0_525
	ds_read_b32 v8, v84
	s_waitcnt lgkmcnt(0)
	v_add_f32_e32 v8, v10, v8
	v_mul_f32_e32 v8, 0x3fb8aa3b, v8
	v_exp_f32_e32 v8, v8
